# residual GEMM epilogues: all 16 base-row loads hoisted to epilogue start with counted vmcnt (no per-row drain behind ssq atomics)
# baseline (speedup 1.0000x reference)
; DI unsigned pk2(float lo, float hi) { f32x2 v = {lo, hi}; return __builtin_bit_cast(unsigned, __builtin_convertvector(v, bf16v2)); }
; DI void ssq_add(float* ssq, int row, float s) { atomicAdd((unsigned*)ssq + row, (unsigned)(s * 1024.f + 0.5f)); }
;     __device__ __forceinline__ void operator()(const f32x4 (&acc)[2][2][4][2], const Unit& u, int wr, int wc, int fr, int fq, const Pre&) const {
;         const int row0 = u.pm * BM + wr * 64 + fr, col0 = u.pn * BM + wc * 32 + 8 * fq;
; #pragma unroll
;         for (int ai = 0; ai < 2; ++ai)
; #pragma unroll
;             for (int m = 0; m < 4; ++m) {
;                 const int row = row0 + ai * HALF + m * 16; const size_t off = (size_t)row * DM + col0; float s = 0.f;
; #pragma unroll
;                 for (int bj = 0; bj < 2; ++bj) {
;                     f32x4 b0, b1;
;                     if (BASE_F32) { const float* bp = (const float*)base + off + bj * HALF; b0 = *(const f32x4*)bp; b1 = *(const f32x4*)(bp + 4); }
;                     else { const u32x4 w = *(const u32x4*)((const bf16_t*)base + off + bj * HALF); b0 = (f32x4){bflo(w.x), bfhi(w.x), bflo(w.y), bfhi(w.y)}; b1 = (f32x4){bflo(w.z), bfhi(w.z), bflo(w.w), bfhi(w.w)}; }
;                     const f32x4 o0 = b0 + acc[ai][bj][m][0] * alpha, o1 = b1 + acc[ai][bj][m][1] * alpha;
;                     if (OUT_F32) { float* op = (float*)out + off + bj * HALF; *(f32x4*)op = o0; *(f32x4*)(op + 4) = o1; }
;                     else { u32x4 w; w.x = pk2(o0[0], o0[1]); w.y = pk2(o0[2], o0[3]); w.z = pk2(o1[0], o1[1]); w.w = pk2(o1[2], o1[3]); *(u32x4*)((bf16_t*)out + off + bj * HALF) = w; }
;                     s += ((o0[0] * o0[0] + o0[1] * o0[1]) + (o0[2] * o0[2] + o0[3] * o0[3])) + ((o1[0] * o1[0] + o1[1] * o1[1]) + (o1[2] * o1[2] + o1[3] * o1[3]));
;                 }
;                 if (ssq) { s += __shfl_xor(s, 16); s += __shfl_xor(s, 32); if (fq == 0) ssq_add(ssq, row, s); }
;             }
.LBB0_811:
	v_lshl_add_u32 v148, s36, 8, v1
	v_ashrrev_i32_e32 v149, 31, v148
	v_readlane_b32 s24, v244, 63
	v_lshl_or_b32 v146, s38, 8, v151
	v_lshlrev_b64 v[156:157], 11, v[148:149]
	v_readlane_b32 s25, v243, 0
	v_ashrrev_i32_e32 v147, 31, v146
	v_xor_b32_e32 v168, 32, v155
	v_lshl_add_u64 v[156:157], s[24:25], 0, v[156:157]
	v_lshl_add_u64 v[166:167], v[146:147], 1, v[156:157]
	v_readlane_b32 s98, v244, 9
	v_readlane_b32 s99, v244, 10
	s_nop 0
	s_add_u32 s98, s98, 0x8600000
	s_addc_u32 s99, s99, 0
	s_nop 1
	v_subrev_u32_e32 v240, s98, v166
	global_load_dwordx4 v[176:179], v240, s[98:99]
	global_load_dwordx4 v[180:183], v240, s[98:99] offset:256
	s_add_u32 s100, s98, 0x8000
	s_addc_u32 s101, s99, 0
	global_load_dwordx4 v[184:187], v240, s[100:101]
	global_load_dwordx4 v[188:191], v240, s[100:101] offset:256
	s_add_u32 s100, s98, 0x10000
	s_addc_u32 s101, s99, 0
	global_load_dwordx4 v[196:199], v240, s[100:101]
	global_load_dwordx4 v[200:203], v240, s[100:101] offset:256
	s_add_u32 s100, s98, 0x18000
	s_addc_u32 s101, s99, 0
	global_load_dwordx4 v[204:207], v240, s[100:101]
	global_load_dwordx4 v[208:211], v240, s[100:101] offset:256
	s_add_u32 s100, s98, 0x40000
	s_addc_u32 s101, s99, 0
	global_load_dwordx4 v[212:215], v240, s[100:101]
	global_load_dwordx4 v[216:219], v240, s[100:101] offset:256
	s_add_u32 s100, s98, 0x48000
	s_addc_u32 s101, s99, 0
	global_load_dwordx4 v[220:223], v240, s[100:101]
	global_load_dwordx4 v[224:227], v240, s[100:101] offset:256
	s_add_u32 s100, s98, 0x50000
	s_addc_u32 s101, s99, 0
	global_load_dwordx4 v[228:231], v240, s[100:101]
	global_load_dwordx4 v[232:235], v240, s[100:101] offset:256
	s_add_u32 s100, s98, 0x58000
	s_addc_u32 s101, s99, 0
	global_load_dwordx4 v[236:239], v240, s[100:101]
	global_load_dwordx4 v[248:251], v240, s[100:101] offset:256
	v_and_b32_e32 v157, 64, v155
	v_xor_b32_e32 v156, 16, v155
	v_add_u32_e32 v157, 64, v157
	v_cmp_lt_i32_e32 vcc, v156, v157
	s_waitcnt vmcnt(14)
	v_and_b32_e32 v169, 0xffff0000, v176
	v_cndmask_b32_e32 v156, v155, v156, vcc
	v_cmp_lt_i32_e32 vcc, v168, v157
	v_lshlrev_b32_e32 v170, 16, v178
	v_and_b32_e32 v171, 0xffff0000, v178
	v_cndmask_b32_e32 v157, v155, v168, vcc
	v_lshlrev_b32_e32 v168, 16, v176
	v_lshlrev_b32_e32 v158, 16, v177
	v_and_b32_e32 v159, 0xffff0000, v177
	v_lshlrev_b32_e32 v160, 16, v179
	v_and_b32_e32 v161, 0xffff0000, v179
	v_lshlrev_b32_e32 v172, 16, v180
	v_and_b32_e32 v173, 0xffff0000, v180
	v_lshlrev_b32_e32 v162, 16, v181
	v_and_b32_e32 v163, 0xffff0000, v181
	v_lshlrev_b32_e32 v174, 16, v182
	v_and_b32_e32 v175, 0xffff0000, v182
	v_lshlrev_b32_e32 v164, 16, v183
	v_and_b32_e32 v165, 0xffff0000, v183
	v_pk_add_f32 v[128:129], v[128:129], v[158:159]
	v_pk_add_f32 v[126:127], v[126:127], v[168:169]
	v_pk_add_f32 v[124:125], v[124:125], v[160:161]
	v_pk_add_f32 v[122:123], v[122:123], v[170:171]
	v_pk_add_f32 v[120:121], v[120:121], v[162:163]
	v_pk_add_f32 v[118:119], v[118:119], v[172:173]
	v_pk_add_f32 v[158:159], v[116:117], v[164:165]
	v_pk_add_f32 v[160:161], v[114:115], v[174:175]
	v_cvt_pk_bf16_f32 v114, v126, v127
	v_cvt_pk_bf16_f32 v115, v128, v129
	v_mul_f32_e32 v116, v127, v127
	v_mul_f32_e32 v117, v129, v129
	v_mul_f32_e32 v127, v123, v123
	v_mul_f32_e32 v129, v125, v125
	v_mul_f32_e32 v162, v119, v119
	v_mul_f32_e32 v163, v121, v121
	v_mul_f32_e32 v164, v161, v161
	v_mul_f32_e32 v165, v159, v159
	v_fmac_f32_e32 v116, v126, v126
	v_fmac_f32_e32 v117, v128, v128
	v_fmac_f32_e32 v127, v122, v122
	v_fmac_f32_e32 v129, v124, v124
	v_fmac_f32_e32 v162, v118, v118
	v_fmac_f32_e32 v163, v120, v120
	v_fmac_f32_e32 v164, v160, v160
	v_fmac_f32_e32 v165, v158, v158
	v_add_f32_e32 v116, v116, v117
	v_add_f32_e32 v117, v127, v129
	v_add_f32_e32 v126, v162, v163
	v_add_f32_e32 v127, v164, v165
	v_add_f32_e32 v116, v116, v117
	v_add_f32_e32 v117, v126, v127
	v_lshlrev_b32_e32 v156, 2, v156
	v_add_f32_e32 v126, v116, v117
	ds_bpermute_b32 v127, v156, v126
	v_cvt_pk_bf16_f32 v116, v122, v123
	v_cvt_pk_bf16_f32 v117, v124, v125
	global_store_dwordx4 v[166:167], v[114:117], off
	v_cvt_pk_bf16_f32 v118, v118, v119
	v_cvt_pk_bf16_f32 v119, v120, v121
	s_waitcnt lgkmcnt(0)
	v_add_f32_e32 v114, v126, v127
	v_lshlrev_b32_e32 v116, 2, v157
	ds_bpermute_b32 v115, v116, v114
	v_cvt_pk_bf16_f32 v120, v160, v161
	v_cvt_pk_bf16_f32 v121, v158, v159
	global_store_dwordx4 v[166:167], v[118:121], off offset:256
	s_and_saveexec_b64 s[36:37], s[0:1]
	s_cbranch_execz .LBB0_813
	s_waitcnt lgkmcnt(0)
	v_add_f32_e32 v114, v114, v115
	v_fma_f32 v114, v114, s51, 0.5
	v_cvt_u32_f32_e32 v117, v114
	v_lshl_add_u64 v[114:115], v[148:149], 2, s[10:11]
	global_atomic_add v[114:115], v117, off
; DI unsigned pk2(float lo, float hi) { f32x2 v = {lo, hi}; return __builtin_bit_cast(unsigned, __builtin_convertvector(v, bf16v2)); }
; DI void ssq_add(float* ssq, int row, float s) { atomicAdd((unsigned*)ssq + row, (unsigned)(s * 1024.f + 0.5f)); }
;     __device__ __forceinline__ void operator()(const f32x4 (&acc)[2][2][4][2], const Unit& u, int wr, int wc, int fr, int fq, const Pre&) const {
;     ...
;             for (int m = 0; m < 4; ++m) {
;                 const int row = row0 + ai * HALF + m * 16; const size_t off = (size_t)row * DM + col0; float s = 0.f;
; #pragma unroll
;                 for (int bj = 0; bj < 2; ++bj) {
;                     f32x4 b0, b1;
;                     if (BASE_F32) { const float* bp = (const float*)base + off + bj * HALF; b0 = *(const f32x4*)bp; b1 = *(const f32x4*)(bp + 4); }
;                     else { const u32x4 w = *(const u32x4*)((const bf16_t*)base + off + bj * HALF); b0 = (f32x4){bflo(w.x), bfhi(w.x), bflo(w.y), bfhi(w.y)}; b1 = (f32x4){bflo(w.z), bfhi(w.z), bflo(w.w), bfhi(w.w)}; }
;                     const f32x4 o0 = b0 + acc[ai][bj][m][0] * alpha, o1 = b1 + acc[ai][bj][m][1] * alpha;
;                     if (OUT_F32) { float* op = (float*)out + off + bj * HALF; *(f32x4*)op = o0; *(f32x4*)(op + 4) = o1; }
;                     else { u32x4 w; w.x = pk2(o0[0], o0[1]); w.y = pk2(o0[2], o0[3]); w.z = pk2(o1[0], o1[1]); w.w = pk2(o1[2], o1[3]); *(u32x4*)((bf16_t*)out + off + bj * HALF) = w; }
;                     s += ((o0[0] * o0[0] + o0[1] * o0[1]) + (o0[2] * o0[2] + o0[3] * o0[3])) + ((o1[0] * o1[0] + o1[1] * o1[1]) + (o1[2] * o1[2] + o1[3] * o1[3]));
;                 }
;                 if (ssq) { s += __shfl_xor(s, 16); s += __shfl_xor(s, 32); if (fq == 0) ssq_add(ssq, row, s); }
.LBB0_813:
	s_or_b64 exec, exec, s[36:37]
	v_or_b32_e32 v114, 16, v148
	s_waitcnt lgkmcnt(0)
	v_ashrrev_i32_e32 v115, 31, v114
	v_readlane_b32 s24, v244, 63
	v_lshlrev_b64 v[118:119], 11, v[114:115]
	v_readlane_b32 s25, v243, 0
	s_nop 1
	v_lshl_add_u64 v[118:119], s[24:25], 0, v[118:119]
	v_lshl_add_u64 v[126:127], v[146:147], 1, v[118:119]
	s_waitcnt vmcnt(16)
	v_lshlrev_b32_e32 v128, 16, v184
	v_and_b32_e32 v129, 0xffff0000, v184
	v_lshlrev_b32_e32 v118, 16, v185
	v_and_b32_e32 v119, 0xffff0000, v185
	v_lshlrev_b32_e32 v158, 16, v186
	v_and_b32_e32 v159, 0xffff0000, v186
	v_lshlrev_b32_e32 v120, 16, v187
	v_and_b32_e32 v121, 0xffff0000, v187
	s_waitcnt vmcnt(15)
	v_lshlrev_b32_e32 v160, 16, v188
	v_and_b32_e32 v161, 0xffff0000, v188
	v_lshlrev_b32_e32 v122, 16, v189
	v_and_b32_e32 v123, 0xffff0000, v189
	v_lshlrev_b32_e32 v162, 16, v190
	v_and_b32_e32 v163, 0xffff0000, v190
	v_lshlrev_b32_e32 v124, 16, v191
	v_and_b32_e32 v125, 0xffff0000, v191
	v_pk_add_f32 v[112:113], v[112:113], v[118:119]
	v_pk_add_f32 v[110:111], v[110:111], v[128:129]
	v_pk_add_f32 v[108:109], v[108:109], v[120:121]
	v_pk_add_f32 v[106:107], v[106:107], v[158:159]
	v_pk_add_f32 v[104:105], v[104:105], v[122:123]
	v_pk_add_f32 v[102:103], v[102:103], v[160:161]
	v_pk_add_f32 v[118:119], v[100:101], v[124:125]
	v_pk_add_f32 v[120:121], v[98:99], v[162:163]
	v_cvt_pk_bf16_f32 v98, v110, v111
	v_cvt_pk_bf16_f32 v99, v112, v113
	v_mul_f32_e32 v100, v111, v111
	v_mul_f32_e32 v101, v113, v113
	v_mul_f32_e32 v111, v107, v107
	v_mul_f32_e32 v113, v109, v109
	v_mul_f32_e32 v117, v103, v103
	v_mul_f32_e32 v122, v105, v105
	v_mul_f32_e32 v123, v121, v121
	v_mul_f32_e32 v124, v119, v119
	v_fmac_f32_e32 v100, v110, v110
	v_fmac_f32_e32 v101, v112, v112
	v_fmac_f32_e32 v111, v106, v106
	v_fmac_f32_e32 v113, v108, v108
	v_fmac_f32_e32 v117, v102, v102
	v_fmac_f32_e32 v122, v104, v104
	v_fmac_f32_e32 v123, v120, v120
	v_fmac_f32_e32 v124, v118, v118
	v_add_f32_e32 v100, v100, v101
	v_add_f32_e32 v101, v111, v113
	v_add_f32_e32 v110, v117, v122
	v_add_f32_e32 v111, v123, v124
	v_add_f32_e32 v100, v100, v101
	v_add_f32_e32 v101, v110, v111
	v_add_f32_e32 v110, v100, v101
	ds_bpermute_b32 v111, v156, v110
	v_cvt_pk_bf16_f32 v100, v106, v107
	v_cvt_pk_bf16_f32 v101, v108, v109
	global_store_dwordx4 v[126:127], v[98:101], off
	s_waitcnt lgkmcnt(0)
	s_nop 0
	v_add_f32_e32 v98, v110, v111
	ds_bpermute_b32 v99, v116, v98
	v_cvt_pk_bf16_f32 v100, v102, v103
	v_cvt_pk_bf16_f32 v101, v104, v105
	v_cvt_pk_bf16_f32 v102, v120, v121
	v_cvt_pk_bf16_f32 v103, v118, v119
	global_store_dwordx4 v[126:127], v[100:103], off offset:256
	s_and_saveexec_b64 s[36:37], s[0:1]
	s_cbranch_execz .LBB0_815
	s_waitcnt lgkmcnt(0)
	v_add_f32_e32 v98, v98, v99
	v_fma_f32 v98, v98, s51, 0.5
	v_cvt_u32_f32_e32 v100, v98
	v_lshl_add_u64 v[98:99], v[114:115], 2, s[10:11]
	global_atomic_add v[98:99], v100, off
.LBB0_815:
	s_or_b64 exec, exec, s[36:37]
	v_or_b32_e32 v98, 32, v148
	s_waitcnt lgkmcnt(0)
	v_ashrrev_i32_e32 v99, 31, v98
	v_readlane_b32 s24, v244, 63
	v_lshlrev_b64 v[100:101], 11, v[98:99]
	v_readlane_b32 s25, v243, 0
	s_nop 1
	v_lshl_add_u64 v[100:101], s[24:25], 0, v[100:101]
	v_lshl_add_u64 v[108:109], v[146:147], 1, v[100:101]
	s_waitcnt vmcnt(17)
	v_lshlrev_b32_e32 v110, 16, v196
	v_and_b32_e32 v111, 0xffff0000, v196
	v_lshlrev_b32_e32 v100, 16, v197
	v_and_b32_e32 v101, 0xffff0000, v197
	v_lshlrev_b32_e32 v112, 16, v198
	v_and_b32_e32 v113, 0xffff0000, v198
	v_lshlrev_b32_e32 v102, 16, v199
	v_and_b32_e32 v103, 0xffff0000, v199
	s_waitcnt vmcnt(16)
	v_lshlrev_b32_e32 v114, 16, v200
	v_and_b32_e32 v115, 0xffff0000, v200
	v_lshlrev_b32_e32 v104, 16, v201
	v_and_b32_e32 v105, 0xffff0000, v201
	v_lshlrev_b32_e32 v118, 16, v202
	v_and_b32_e32 v119, 0xffff0000, v202
	v_lshlrev_b32_e32 v106, 16, v203
	v_and_b32_e32 v107, 0xffff0000, v203
	v_pk_add_f32 v[96:97], v[96:97], v[100:101]
	v_pk_add_f32 v[94:95], v[94:95], v[110:111]
	v_pk_add_f32 v[92:93], v[92:93], v[102:103]
	v_pk_add_f32 v[90:91], v[90:91], v[112:113]
	v_pk_add_f32 v[88:89], v[88:89], v[104:105]
	v_pk_add_f32 v[86:87], v[86:87], v[114:115]
	v_pk_add_f32 v[100:101], v[84:85], v[106:107]
	v_pk_add_f32 v[102:103], v[82:83], v[118:119]
	v_cvt_pk_bf16_f32 v82, v94, v95
	v_cvt_pk_bf16_f32 v83, v96, v97
	v_mul_f32_e32 v84, v95, v95
	v_mul_f32_e32 v85, v97, v97
	v_mul_f32_e32 v95, v91, v91
	v_mul_f32_e32 v97, v93, v93
	v_mul_f32_e32 v104, v87, v87
	v_mul_f32_e32 v105, v89, v89
	v_mul_f32_e32 v106, v103, v103
	v_mul_f32_e32 v107, v101, v101
	v_fmac_f32_e32 v84, v94, v94
	v_fmac_f32_e32 v85, v96, v96
	v_fmac_f32_e32 v95, v90, v90
	v_fmac_f32_e32 v97, v92, v92
	v_fmac_f32_e32 v104, v86, v86
	v_fmac_f32_e32 v105, v88, v88
	v_fmac_f32_e32 v106, v102, v102
	v_fmac_f32_e32 v107, v100, v100
	v_add_f32_e32 v84, v84, v85
	v_add_f32_e32 v85, v95, v97
	v_add_f32_e32 v94, v104, v105
	v_add_f32_e32 v95, v106, v107
	v_add_f32_e32 v84, v84, v85
	v_add_f32_e32 v85, v94, v95
	v_add_f32_e32 v94, v84, v85
	ds_bpermute_b32 v95, v156, v94
	v_cvt_pk_bf16_f32 v84, v90, v91
	v_cvt_pk_bf16_f32 v85, v92, v93
	global_store_dwordx4 v[108:109], v[82:85], off
	s_waitcnt lgkmcnt(0)
	s_nop 0
	v_add_f32_e32 v82, v94, v95
	ds_bpermute_b32 v83, v116, v82
	v_cvt_pk_bf16_f32 v84, v86, v87
	v_cvt_pk_bf16_f32 v85, v88, v89
	v_cvt_pk_bf16_f32 v86, v102, v103
	v_cvt_pk_bf16_f32 v87, v100, v101
	global_store_dwordx4 v[108:109], v[84:87], off offset:256
	s_and_saveexec_b64 s[36:37], s[0:1]
	s_cbranch_execz .LBB0_817
	s_waitcnt lgkmcnt(0)
	v_add_f32_e32 v82, v82, v83
	v_fma_f32 v82, v82, s51, 0.5
	v_cvt_u32_f32_e32 v84, v82
	v_lshl_add_u64 v[82:83], v[98:99], 2, s[10:11]
	global_atomic_add v[82:83], v84, off
; DI unsigned pk2(float lo, float hi) { f32x2 v = {lo, hi}; return __builtin_bit_cast(unsigned, __builtin_convertvector(v, bf16v2)); }
; DI void ssq_add(float* ssq, int row, float s) { atomicAdd((unsigned*)ssq + row, (unsigned)(s * 1024.f + 0.5f)); }
;     __device__ __forceinline__ void operator()(const f32x4 (&acc)[2][2][4][2], const Unit& u, int wr, int wc, int fr, int fq, const Pre&) const {
;     ...
;             for (int m = 0; m < 4; ++m) {
;                 const int row = row0 + ai * HALF + m * 16; const size_t off = (size_t)row * DM + col0; float s = 0.f;
; #pragma unroll
;                 for (int bj = 0; bj < 2; ++bj) {
;                     f32x4 b0, b1;
;                     if (BASE_F32) { const float* bp = (const float*)base + off + bj * HALF; b0 = *(const f32x4*)bp; b1 = *(const f32x4*)(bp + 4); }
;                     else { const u32x4 w = *(const u32x4*)((const bf16_t*)base + off + bj * HALF); b0 = (f32x4){bflo(w.x), bfhi(w.x), bflo(w.y), bfhi(w.y)}; b1 = (f32x4){bflo(w.z), bfhi(w.z), bflo(w.w), bfhi(w.w)}; }
;                     const f32x4 o0 = b0 + acc[ai][bj][m][0] * alpha, o1 = b1 + acc[ai][bj][m][1] * alpha;
;                     if (OUT_F32) { float* op = (float*)out + off + bj * HALF; *(f32x4*)op = o0; *(f32x4*)(op + 4) = o1; }
;                     else { u32x4 w; w.x = pk2(o0[0], o0[1]); w.y = pk2(o0[2], o0[3]); w.z = pk2(o1[0], o1[1]); w.w = pk2(o1[2], o1[3]); *(u32x4*)((bf16_t*)out + off + bj * HALF) = w; }
;                     s += ((o0[0] * o0[0] + o0[1] * o0[1]) + (o0[2] * o0[2] + o0[3] * o0[3])) + ((o1[0] * o1[0] + o1[1] * o1[1]) + (o1[2] * o1[2] + o1[3] * o1[3]));
;                 }
;                 if (ssq) { s += __shfl_xor(s, 16); s += __shfl_xor(s, 32); if (fq == 0) ssq_add(ssq, row, s); }
.LBB0_817:
	s_or_b64 exec, exec, s[36:37]
	v_or_b32_e32 v82, 48, v148
	s_waitcnt lgkmcnt(0)
	v_ashrrev_i32_e32 v83, 31, v82
	v_readlane_b32 s24, v244, 63
	v_lshlrev_b64 v[84:85], 11, v[82:83]
	v_readlane_b32 s25, v243, 0
	s_nop 1
	v_lshl_add_u64 v[84:85], s[24:25], 0, v[84:85]
	v_lshl_add_u64 v[92:93], v[146:147], 1, v[84:85]
	s_waitcnt vmcnt(18)
	v_lshlrev_b32_e32 v94, 16, v204
	v_and_b32_e32 v95, 0xffff0000, v204
	v_lshlrev_b32_e32 v84, 16, v205
	v_and_b32_e32 v85, 0xffff0000, v205
	v_lshlrev_b32_e32 v96, 16, v206
	v_and_b32_e32 v97, 0xffff0000, v206
	v_lshlrev_b32_e32 v86, 16, v207
	v_and_b32_e32 v87, 0xffff0000, v207
	s_waitcnt vmcnt(17)
	v_lshlrev_b32_e32 v98, 16, v208
	v_and_b32_e32 v99, 0xffff0000, v208
	v_lshlrev_b32_e32 v88, 16, v209
	v_and_b32_e32 v89, 0xffff0000, v209
	v_lshlrev_b32_e32 v100, 16, v210
	v_and_b32_e32 v101, 0xffff0000, v210
	v_lshlrev_b32_e32 v90, 16, v211
	v_and_b32_e32 v91, 0xffff0000, v211
	v_pk_add_f32 v[80:81], v[80:81], v[84:85]
	v_pk_add_f32 v[78:79], v[78:79], v[94:95]
	v_pk_add_f32 v[76:77], v[76:77], v[86:87]
	v_pk_add_f32 v[74:75], v[74:75], v[96:97]
	v_pk_add_f32 v[72:73], v[72:73], v[88:89]
	v_pk_add_f32 v[70:71], v[70:71], v[98:99]
	v_pk_add_f32 v[84:85], v[68:69], v[90:91]
	v_pk_add_f32 v[86:87], v[66:67], v[100:101]
	v_cvt_pk_bf16_f32 v66, v78, v79
	v_cvt_pk_bf16_f32 v67, v80, v81
	v_mul_f32_e32 v68, v79, v79
	v_mul_f32_e32 v69, v81, v81
	v_mul_f32_e32 v79, v75, v75
	v_mul_f32_e32 v81, v77, v77
	v_mul_f32_e32 v88, v71, v71
	v_mul_f32_e32 v89, v73, v73
	v_mul_f32_e32 v90, v87, v87
	v_mul_f32_e32 v91, v85, v85
	v_fmac_f32_e32 v68, v78, v78
	v_fmac_f32_e32 v69, v80, v80
	v_fmac_f32_e32 v79, v74, v74
	v_fmac_f32_e32 v81, v76, v76
	v_fmac_f32_e32 v88, v70, v70
	v_fmac_f32_e32 v89, v72, v72
	v_fmac_f32_e32 v90, v86, v86
	v_fmac_f32_e32 v91, v84, v84
	v_add_f32_e32 v68, v68, v69
	v_add_f32_e32 v69, v79, v81
	v_add_f32_e32 v78, v88, v89
	v_add_f32_e32 v79, v90, v91
	v_add_f32_e32 v68, v68, v69
	v_add_f32_e32 v69, v78, v79
	v_add_f32_e32 v78, v68, v69
	ds_bpermute_b32 v79, v156, v78
	v_cvt_pk_bf16_f32 v68, v74, v75
	v_cvt_pk_bf16_f32 v69, v76, v77
	global_store_dwordx4 v[92:93], v[66:69], off
	s_waitcnt lgkmcnt(0)
	s_nop 0
	v_add_f32_e32 v66, v78, v79
	ds_bpermute_b32 v67, v116, v66
	v_cvt_pk_bf16_f32 v68, v70, v71
	v_cvt_pk_bf16_f32 v69, v72, v73
	v_cvt_pk_bf16_f32 v70, v86, v87
	v_cvt_pk_bf16_f32 v71, v84, v85
	global_store_dwordx4 v[92:93], v[68:71], off offset:256
	s_and_saveexec_b64 s[36:37], s[0:1]
	s_cbranch_execz .LBB0_819
	s_waitcnt lgkmcnt(0)
	v_add_f32_e32 v66, v66, v67
	v_fma_f32 v66, v66, s51, 0.5
	v_cvt_u32_f32_e32 v68, v66
	v_lshl_add_u64 v[66:67], v[82:83], 2, s[10:11]
	global_atomic_add v[66:67], v68, off
.LBB0_819:
	s_or_b64 exec, exec, s[36:37]
	v_add_u32_e32 v66, 0x80, v148
	s_waitcnt lgkmcnt(0)
	v_ashrrev_i32_e32 v67, 31, v66
	v_readlane_b32 s24, v244, 63
	v_lshlrev_b64 v[68:69], 11, v[66:67]
	v_readlane_b32 s25, v243, 0
	s_nop 1
	v_lshl_add_u64 v[68:69], s[24:25], 0, v[68:69]
	v_lshl_add_u64 v[76:77], v[146:147], 1, v[68:69]
	s_waitcnt vmcnt(19)
	v_lshlrev_b32_e32 v78, 16, v212
	v_and_b32_e32 v79, 0xffff0000, v212
	v_lshlrev_b32_e32 v68, 16, v213
	v_and_b32_e32 v69, 0xffff0000, v213
	v_lshlrev_b32_e32 v80, 16, v214
	v_and_b32_e32 v81, 0xffff0000, v214
	v_lshlrev_b32_e32 v70, 16, v215
	v_and_b32_e32 v71, 0xffff0000, v215
	s_waitcnt vmcnt(18)
	v_lshlrev_b32_e32 v82, 16, v216
	v_and_b32_e32 v83, 0xffff0000, v216
	v_lshlrev_b32_e32 v72, 16, v217
	v_and_b32_e32 v73, 0xffff0000, v217
	v_lshlrev_b32_e32 v84, 16, v218
	v_and_b32_e32 v85, 0xffff0000, v218
	v_lshlrev_b32_e32 v74, 16, v219
	v_and_b32_e32 v75, 0xffff0000, v219
	v_pk_add_f32 v[64:65], v[64:65], v[68:69]
	v_pk_add_f32 v[62:63], v[62:63], v[78:79]
	v_pk_add_f32 v[60:61], v[60:61], v[70:71]
	v_pk_add_f32 v[58:59], v[58:59], v[80:81]
	v_pk_add_f32 v[56:57], v[56:57], v[72:73]
	v_pk_add_f32 v[54:55], v[54:55], v[82:83]
	v_pk_add_f32 v[68:69], v[52:53], v[74:75]
	v_pk_add_f32 v[70:71], v[50:51], v[84:85]
	v_cvt_pk_bf16_f32 v50, v62, v63
	v_cvt_pk_bf16_f32 v51, v64, v65
	v_mul_f32_e32 v52, v63, v63
	v_mul_f32_e32 v53, v65, v65
	v_mul_f32_e32 v63, v59, v59
	v_mul_f32_e32 v65, v61, v61
	v_mul_f32_e32 v72, v55, v55
	v_mul_f32_e32 v73, v57, v57
	v_mul_f32_e32 v74, v71, v71
	v_mul_f32_e32 v75, v69, v69
	v_fmac_f32_e32 v52, v62, v62
	v_fmac_f32_e32 v53, v64, v64
	v_fmac_f32_e32 v63, v58, v58
	v_fmac_f32_e32 v65, v60, v60
	v_fmac_f32_e32 v72, v54, v54
	v_fmac_f32_e32 v73, v56, v56
	v_fmac_f32_e32 v74, v70, v70
	v_fmac_f32_e32 v75, v68, v68
	v_add_f32_e32 v52, v52, v53
	v_add_f32_e32 v53, v63, v65
	v_add_f32_e32 v62, v72, v73
	v_add_f32_e32 v63, v74, v75
	v_add_f32_e32 v52, v52, v53
	v_add_f32_e32 v53, v62, v63
	v_add_f32_e32 v62, v52, v53
	ds_bpermute_b32 v63, v156, v62
	v_cvt_pk_bf16_f32 v52, v58, v59
	v_cvt_pk_bf16_f32 v53, v60, v61
	global_store_dwordx4 v[76:77], v[50:53], off
	s_waitcnt lgkmcnt(0)
	s_nop 0
	v_add_f32_e32 v50, v62, v63
	ds_bpermute_b32 v51, v116, v50
	v_cvt_pk_bf16_f32 v52, v54, v55
	v_cvt_pk_bf16_f32 v53, v56, v57
	v_cvt_pk_bf16_f32 v54, v70, v71
	v_cvt_pk_bf16_f32 v55, v68, v69
	global_store_dwordx4 v[76:77], v[52:55], off offset:256
	s_and_saveexec_b64 s[36:37], s[0:1]
	s_cbranch_execz .LBB0_821
	s_waitcnt lgkmcnt(0)
	v_add_f32_e32 v50, v50, v51
	v_fma_f32 v50, v50, s51, 0.5
	v_cvt_u32_f32_e32 v52, v50
	v_lshl_add_u64 v[50:51], v[66:67], 2, s[10:11]
	global_atomic_add v[50:51], v52, off
; DI unsigned pk2(float lo, float hi) { f32x2 v = {lo, hi}; return __builtin_bit_cast(unsigned, __builtin_convertvector(v, bf16v2)); }
; DI void ssq_add(float* ssq, int row, float s) { atomicAdd((unsigned*)ssq + row, (unsigned)(s * 1024.f + 0.5f)); }
;     __device__ __forceinline__ void operator()(const f32x4 (&acc)[2][2][4][2], const Unit& u, int wr, int wc, int fr, int fq, const Pre&) const {
;     ...
;             for (int m = 0; m < 4; ++m) {
;                 const int row = row0 + ai * HALF + m * 16; const size_t off = (size_t)row * DM + col0; float s = 0.f;
; #pragma unroll
;                 for (int bj = 0; bj < 2; ++bj) {
;                     f32x4 b0, b1;
;                     if (BASE_F32) { const float* bp = (const float*)base + off + bj * HALF; b0 = *(const f32x4*)bp; b1 = *(const f32x4*)(bp + 4); }
;                     else { const u32x4 w = *(const u32x4*)((const bf16_t*)base + off + bj * HALF); b0 = (f32x4){bflo(w.x), bfhi(w.x), bflo(w.y), bfhi(w.y)}; b1 = (f32x4){bflo(w.z), bfhi(w.z), bflo(w.w), bfhi(w.w)}; }
;                     const f32x4 o0 = b0 + acc[ai][bj][m][0] * alpha, o1 = b1 + acc[ai][bj][m][1] * alpha;
;                     if (OUT_F32) { float* op = (float*)out + off + bj * HALF; *(f32x4*)op = o0; *(f32x4*)(op + 4) = o1; }
;                     else { u32x4 w; w.x = pk2(o0[0], o0[1]); w.y = pk2(o0[2], o0[3]); w.z = pk2(o1[0], o1[1]); w.w = pk2(o1[2], o1[3]); *(u32x4*)((bf16_t*)out + off + bj * HALF) = w; }
;                     s += ((o0[0] * o0[0] + o0[1] * o0[1]) + (o0[2] * o0[2] + o0[3] * o0[3])) + ((o1[0] * o1[0] + o1[1] * o1[1]) + (o1[2] * o1[2] + o1[3] * o1[3]));
;                 }
;                 if (ssq) { s += __shfl_xor(s, 16); s += __shfl_xor(s, 32); if (fq == 0) ssq_add(ssq, row, s); }
.LBB0_821:
	s_or_b64 exec, exec, s[36:37]
	v_add_u32_e32 v50, 0x90, v148
	s_waitcnt lgkmcnt(0)
	v_ashrrev_i32_e32 v51, 31, v50
	v_readlane_b32 s24, v244, 63
	v_lshlrev_b64 v[52:53], 11, v[50:51]
	v_readlane_b32 s25, v243, 0
	s_nop 1
	v_lshl_add_u64 v[52:53], s[24:25], 0, v[52:53]
	v_lshl_add_u64 v[60:61], v[146:147], 1, v[52:53]
	s_waitcnt vmcnt(20)
	v_lshlrev_b32_e32 v62, 16, v220
	v_and_b32_e32 v63, 0xffff0000, v220
	v_lshlrev_b32_e32 v52, 16, v221
	v_and_b32_e32 v53, 0xffff0000, v221
	v_lshlrev_b32_e32 v64, 16, v222
	v_and_b32_e32 v65, 0xffff0000, v222
	v_lshlrev_b32_e32 v54, 16, v223
	v_and_b32_e32 v55, 0xffff0000, v223
	s_waitcnt vmcnt(19)
	v_lshlrev_b32_e32 v66, 16, v224
	v_and_b32_e32 v67, 0xffff0000, v224
	v_lshlrev_b32_e32 v56, 16, v225
	v_and_b32_e32 v57, 0xffff0000, v225
	v_lshlrev_b32_e32 v68, 16, v226
	v_and_b32_e32 v69, 0xffff0000, v226
	v_lshlrev_b32_e32 v58, 16, v227
	v_and_b32_e32 v59, 0xffff0000, v227
	v_pk_add_f32 v[48:49], v[48:49], v[52:53]
	v_pk_add_f32 v[46:47], v[46:47], v[62:63]
	v_pk_add_f32 v[44:45], v[44:45], v[54:55]
	v_pk_add_f32 v[42:43], v[42:43], v[64:65]
	v_pk_add_f32 v[40:41], v[40:41], v[56:57]
	v_pk_add_f32 v[38:39], v[38:39], v[66:67]
	v_pk_add_f32 v[52:53], v[36:37], v[58:59]
	v_pk_add_f32 v[54:55], v[34:35], v[68:69]
	v_cvt_pk_bf16_f32 v34, v46, v47
	v_cvt_pk_bf16_f32 v35, v48, v49
	v_mul_f32_e32 v36, v47, v47
	v_mul_f32_e32 v37, v49, v49
	v_mul_f32_e32 v47, v43, v43
	v_mul_f32_e32 v49, v45, v45
	v_mul_f32_e32 v56, v39, v39
	v_mul_f32_e32 v57, v41, v41
	v_mul_f32_e32 v58, v55, v55
	v_mul_f32_e32 v59, v53, v53
	v_fmac_f32_e32 v36, v46, v46
	v_fmac_f32_e32 v37, v48, v48
	v_fmac_f32_e32 v47, v42, v42
	v_fmac_f32_e32 v49, v44, v44
	v_fmac_f32_e32 v56, v38, v38
	v_fmac_f32_e32 v57, v40, v40
	v_fmac_f32_e32 v58, v54, v54
	v_fmac_f32_e32 v59, v52, v52
	v_add_f32_e32 v36, v36, v37
	v_add_f32_e32 v37, v47, v49
	v_add_f32_e32 v46, v56, v57
	v_add_f32_e32 v47, v58, v59
	v_add_f32_e32 v36, v36, v37
	v_add_f32_e32 v37, v46, v47
	v_add_f32_e32 v46, v36, v37
	ds_bpermute_b32 v47, v156, v46
	v_cvt_pk_bf16_f32 v36, v42, v43
	v_cvt_pk_bf16_f32 v37, v44, v45
	global_store_dwordx4 v[60:61], v[34:37], off
	s_waitcnt lgkmcnt(0)
	s_nop 0
	v_add_f32_e32 v34, v46, v47
	ds_bpermute_b32 v35, v116, v34
	v_cvt_pk_bf16_f32 v36, v38, v39
	v_cvt_pk_bf16_f32 v37, v40, v41
	v_cvt_pk_bf16_f32 v38, v54, v55
	v_cvt_pk_bf16_f32 v39, v52, v53
	global_store_dwordx4 v[60:61], v[36:39], off offset:256
	s_and_saveexec_b64 s[36:37], s[0:1]
	s_cbranch_execz .LBB0_823
	s_waitcnt lgkmcnt(0)
	v_add_f32_e32 v34, v34, v35
	v_fma_f32 v34, v34, s51, 0.5
	v_cvt_u32_f32_e32 v36, v34
	v_lshl_add_u64 v[34:35], v[50:51], 2, s[10:11]
	global_atomic_add v[34:35], v36, off
; DI unsigned pk2(float lo, float hi) { f32x2 v = {lo, hi}; return __builtin_bit_cast(unsigned, __builtin_convertvector(v, bf16v2)); }
; DI void ssq_add(float* ssq, int row, float s) { atomicAdd((unsigned*)ssq + row, (unsigned)(s * 1024.f + 0.5f)); }
;     __device__ __forceinline__ void operator()(const f32x4 (&acc)[2][2][4][2], const Unit& u, int wr, int wc, int fr, int fq, const Pre&) const {
;     ...
;             for (int m = 0; m < 4; ++m) {
;                 const int row = row0 + ai * HALF + m * 16; const size_t off = (size_t)row * DM + col0; float s = 0.f;
; #pragma unroll
;                 for (int bj = 0; bj < 2; ++bj) {
;                     f32x4 b0, b1;
;                     if (BASE_F32) { const float* bp = (const float*)base + off + bj * HALF; b0 = *(const f32x4*)bp; b1 = *(const f32x4*)(bp + 4); }
;                     else { const u32x4 w = *(const u32x4*)((const bf16_t*)base + off + bj * HALF); b0 = (f32x4){bflo(w.x), bfhi(w.x), bflo(w.y), bfhi(w.y)}; b1 = (f32x4){bflo(w.z), bfhi(w.z), bflo(w.w), bfhi(w.w)}; }
;                     const f32x4 o0 = b0 + acc[ai][bj][m][0] * alpha, o1 = b1 + acc[ai][bj][m][1] * alpha;
;                     if (OUT_F32) { float* op = (float*)out + off + bj * HALF; *(f32x4*)op = o0; *(f32x4*)(op + 4) = o1; }
;                     else { u32x4 w; w.x = pk2(o0[0], o0[1]); w.y = pk2(o0[2], o0[3]); w.z = pk2(o1[0], o1[1]); w.w = pk2(o1[2], o1[3]); *(u32x4*)((bf16_t*)out + off + bj * HALF) = w; }
;                     s += ((o0[0] * o0[0] + o0[1] * o0[1]) + (o0[2] * o0[2] + o0[3] * o0[3])) + ((o1[0] * o1[0] + o1[1] * o1[1]) + (o1[2] * o1[2] + o1[3] * o1[3]));
;                 }
;                 if (ssq) { s += __shfl_xor(s, 16); s += __shfl_xor(s, 32); if (fq == 0) ssq_add(ssq, row, s); }
.LBB0_823:
	s_or_b64 exec, exec, s[36:37]
	v_add_u32_e32 v34, 0xa0, v148
	s_waitcnt lgkmcnt(0)
	v_ashrrev_i32_e32 v35, 31, v34
	v_readlane_b32 s24, v244, 63
	v_lshlrev_b64 v[36:37], 11, v[34:35]
	v_readlane_b32 s25, v243, 0
	s_nop 1
	v_lshl_add_u64 v[36:37], s[24:25], 0, v[36:37]
	v_lshl_add_u64 v[44:45], v[146:147], 1, v[36:37]
	s_waitcnt vmcnt(21)
	v_lshlrev_b32_e32 v46, 16, v228
	v_and_b32_e32 v47, 0xffff0000, v228
	v_lshlrev_b32_e32 v36, 16, v229
	v_and_b32_e32 v37, 0xffff0000, v229
	v_lshlrev_b32_e32 v48, 16, v230
	v_and_b32_e32 v49, 0xffff0000, v230
	v_lshlrev_b32_e32 v38, 16, v231
	v_and_b32_e32 v39, 0xffff0000, v231
	s_waitcnt vmcnt(20)
	v_lshlrev_b32_e32 v50, 16, v232
	v_and_b32_e32 v51, 0xffff0000, v232
	v_lshlrev_b32_e32 v40, 16, v233
	v_and_b32_e32 v41, 0xffff0000, v233
	v_lshlrev_b32_e32 v52, 16, v234
	v_and_b32_e32 v53, 0xffff0000, v234
	v_lshlrev_b32_e32 v42, 16, v235
	v_and_b32_e32 v43, 0xffff0000, v235
	v_pk_add_f32 v[32:33], v[32:33], v[36:37]
	v_pk_add_f32 v[30:31], v[30:31], v[46:47]
	v_pk_add_f32 v[28:29], v[28:29], v[38:39]
	v_pk_add_f32 v[26:27], v[26:27], v[48:49]
	v_pk_add_f32 v[24:25], v[24:25], v[40:41]
	v_pk_add_f32 v[22:23], v[22:23], v[50:51]
	v_pk_add_f32 v[36:37], v[20:21], v[42:43]
	v_pk_add_f32 v[38:39], v[18:19], v[52:53]
	v_cvt_pk_bf16_f32 v18, v30, v31
	v_cvt_pk_bf16_f32 v19, v32, v33
	v_mul_f32_e32 v20, v31, v31
	v_mul_f32_e32 v21, v33, v33
	v_mul_f32_e32 v31, v27, v27
	v_mul_f32_e32 v33, v29, v29
	v_mul_f32_e32 v40, v23, v23
	v_mul_f32_e32 v41, v25, v25
	v_mul_f32_e32 v42, v39, v39
	v_mul_f32_e32 v43, v37, v37
	v_fmac_f32_e32 v20, v30, v30
	v_fmac_f32_e32 v21, v32, v32
	v_fmac_f32_e32 v31, v26, v26
	v_fmac_f32_e32 v33, v28, v28
	v_fmac_f32_e32 v40, v22, v22
	v_fmac_f32_e32 v41, v24, v24
	v_fmac_f32_e32 v42, v38, v38
	v_fmac_f32_e32 v43, v36, v36
	v_add_f32_e32 v20, v20, v21
	v_add_f32_e32 v21, v31, v33
	v_add_f32_e32 v30, v40, v41
	v_add_f32_e32 v31, v42, v43
	v_add_f32_e32 v20, v20, v21
	v_add_f32_e32 v21, v30, v31
	v_add_f32_e32 v30, v20, v21
	ds_bpermute_b32 v31, v156, v30
	v_cvt_pk_bf16_f32 v20, v26, v27
	v_cvt_pk_bf16_f32 v21, v28, v29
	global_store_dwordx4 v[44:45], v[18:21], off
	s_waitcnt lgkmcnt(0)
	s_nop 0
	v_add_f32_e32 v18, v30, v31
	ds_bpermute_b32 v19, v116, v18
	v_cvt_pk_bf16_f32 v20, v22, v23
	v_cvt_pk_bf16_f32 v21, v24, v25
	v_cvt_pk_bf16_f32 v22, v38, v39
	v_cvt_pk_bf16_f32 v23, v36, v37
	global_store_dwordx4 v[44:45], v[20:23], off offset:256
	s_and_saveexec_b64 s[36:37], s[0:1]
	s_cbranch_execz .LBB0_825
	s_waitcnt lgkmcnt(0)
	v_add_f32_e32 v18, v18, v19
	v_fma_f32 v18, v18, s51, 0.5
	v_cvt_u32_f32_e32 v20, v18
	v_lshl_add_u64 v[18:19], v[34:35], 2, s[10:11]
	global_atomic_add v[18:19], v20, off
.LBB0_825:
	s_or_b64 exec, exec, s[36:37]
	v_add_u32_e32 v18, 0xb0, v148
	s_waitcnt lgkmcnt(0)
	v_ashrrev_i32_e32 v19, 31, v18
	v_readlane_b32 s24, v244, 63
	v_lshlrev_b64 v[20:21], 11, v[18:19]
	v_readlane_b32 s25, v243, 0
	s_nop 1
	v_lshl_add_u64 v[20:21], s[24:25], 0, v[20:21]
	v_lshl_add_u64 v[28:29], v[146:147], 1, v[20:21]
	s_waitcnt vmcnt(22)
	v_lshlrev_b32_e32 v30, 16, v236
	v_and_b32_e32 v31, 0xffff0000, v236
	v_lshlrev_b32_e32 v20, 16, v237
	v_and_b32_e32 v21, 0xffff0000, v237
	v_lshlrev_b32_e32 v32, 16, v238
	v_and_b32_e32 v33, 0xffff0000, v238
	v_lshlrev_b32_e32 v22, 16, v239
	v_and_b32_e32 v23, 0xffff0000, v239
	s_waitcnt vmcnt(21)
	v_lshlrev_b32_e32 v34, 16, v248
	v_and_b32_e32 v35, 0xffff0000, v248
	v_lshlrev_b32_e32 v24, 16, v249
	v_and_b32_e32 v25, 0xffff0000, v249
	v_lshlrev_b32_e32 v36, 16, v250
	v_and_b32_e32 v37, 0xffff0000, v250
	v_lshlrev_b32_e32 v26, 16, v251
	v_and_b32_e32 v27, 0xffff0000, v251
	v_pk_add_f32 v[16:17], v[16:17], v[20:21]
	v_pk_add_f32 v[14:15], v[14:15], v[30:31]
	v_pk_add_f32 v[12:13], v[12:13], v[22:23]
	v_pk_add_f32 v[10:11], v[10:11], v[32:33]
	v_pk_add_f32 v[8:9], v[8:9], v[24:25]
	v_pk_add_f32 v[6:7], v[6:7], v[34:35]
	v_pk_add_f32 v[20:21], v[4:5], v[26:27]
	v_pk_add_f32 v[22:23], v[2:3], v[36:37]
	v_cvt_pk_bf16_f32 v2, v14, v15
	v_cvt_pk_bf16_f32 v3, v16, v17
	v_mul_f32_e32 v4, v15, v15
	v_mul_f32_e32 v5, v17, v17
	v_mul_f32_e32 v15, v11, v11
	v_mul_f32_e32 v17, v13, v13
	v_mul_f32_e32 v24, v7, v7
	v_mul_f32_e32 v25, v9, v9
	v_mul_f32_e32 v26, v23, v23
	v_mul_f32_e32 v27, v21, v21
	v_fmac_f32_e32 v4, v14, v14
	v_fmac_f32_e32 v5, v16, v16
	v_fmac_f32_e32 v15, v10, v10
	v_fmac_f32_e32 v17, v12, v12
	v_fmac_f32_e32 v24, v6, v6
	v_fmac_f32_e32 v25, v8, v8
	v_fmac_f32_e32 v26, v22, v22
	v_fmac_f32_e32 v27, v20, v20
	v_add_f32_e32 v4, v4, v5
	v_add_f32_e32 v5, v15, v17
	v_add_f32_e32 v14, v24, v25
	v_add_f32_e32 v15, v26, v27
	v_add_f32_e32 v4, v4, v5
	v_add_f32_e32 v5, v14, v15
	v_add_f32_e32 v14, v4, v5
	ds_bpermute_b32 v15, v156, v14
	v_cvt_pk_bf16_f32 v4, v10, v11
	v_cvt_pk_bf16_f32 v5, v12, v13
	global_store_dwordx4 v[28:29], v[2:5], off
	s_waitcnt lgkmcnt(0)
	s_nop 0
	v_add_f32_e32 v2, v14, v15
	ds_bpermute_b32 v3, v116, v2
	v_cvt_pk_bf16_f32 v4, v6, v7
	v_cvt_pk_bf16_f32 v5, v8, v9
	v_cvt_pk_bf16_f32 v6, v22, v23
	v_cvt_pk_bf16_f32 v7, v20, v21
	global_store_dwordx4 v[28:29], v[4:7], off offset:256
	s_and_saveexec_b64 s[36:37], s[0:1]
	s_cbranch_execz .LBB0_827
	s_waitcnt lgkmcnt(0)
	v_add_f32_e32 v2, v2, v3
	v_fma_f32 v2, v2, s51, 0.5
	v_cvt_u32_f32_e32 v4, v2
	v_lshl_add_u64 v[2:3], v[18:19], 2, s[10:11]
	global_atomic_add v[2:3], v4, off

; DI unsigned pk2(float lo, float hi) { f32x2 v = {lo, hi}; return __builtin_bit_cast(unsigned, __builtin_convertvector(v, bf16v2)); }
; DI void ssq_add(float* ssq, int row, float s) { atomicAdd((unsigned*)ssq + row, (unsigned)(s * 1024.f + 0.5f)); }
;     __device__ __forceinline__ void operator()(const f32x4 (&acc)[2][2][4][2], const Unit& u, int wr, int wc, int fr, int fq, const Pre&) const {
;         const int row0 = u.pm * BM + wr * 64 + fr, col0 = u.pn * BM + wc * 32 + 8 * fq;
; #pragma unroll
;         for (int ai = 0; ai < 2; ++ai)
; #pragma unroll
;             for (int m = 0; m < 4; ++m) {
;                 const int row = row0 + ai * HALF + m * 16; const size_t off = (size_t)row * DM + col0; float s = 0.f;
; #pragma unroll
;                 for (int bj = 0; bj < 2; ++bj) {
;                     f32x4 b0, b1;
;                     if (BASE_F32) { const float* bp = (const float*)base + off + bj * HALF; b0 = *(const f32x4*)bp; b1 = *(const f32x4*)(bp + 4); }
;                     else { const u32x4 w = *(const u32x4*)((const bf16_t*)base + off + bj * HALF); b0 = (f32x4){bflo(w.x), bfhi(w.x), bflo(w.y), bfhi(w.y)}; b1 = (f32x4){bflo(w.z), bfhi(w.z), bflo(w.w), bfhi(w.w)}; }
;                     const f32x4 o0 = b0 + acc[ai][bj][m][0] * alpha, o1 = b1 + acc[ai][bj][m][1] * alpha;
;                     if (OUT_F32) { float* op = (float*)out + off + bj * HALF; *(f32x4*)op = o0; *(f32x4*)(op + 4) = o1; }
;                     else { u32x4 w; w.x = pk2(o0[0], o0[1]); w.y = pk2(o0[2], o0[3]); w.z = pk2(o1[0], o1[1]); w.w = pk2(o1[2], o1[3]); *(u32x4*)((bf16_t*)out + off + bj * HALF) = w; }
;                     s += ((o0[0] * o0[0] + o0[1] * o0[1]) + (o0[2] * o0[2] + o0[3] * o0[3])) + ((o1[0] * o1[0] + o1[1] * o1[1]) + (o1[2] * o1[2] + o1[3] * o1[3]));
;                 }
;                 if (ssq) { s += __shfl_xor(s, 16); s += __shfl_xor(s, 32); if (fq == 0) ssq_add(ssq, row, s); }
.LBB0_1041:
	v_lshl_add_u32 v148, s36, 8, v1
	v_ashrrev_i32_e32 v149, 31, v148
	v_readlane_b32 s24, v244, 63
	v_lshl_or_b32 v146, s38, 8, v151
	v_lshlrev_b64 v[156:157], 11, v[148:149]
	v_readlane_b32 s25, v243, 0
	v_ashrrev_i32_e32 v147, 31, v146
	v_xor_b32_e32 v168, 32, v155
	v_lshl_add_u64 v[156:157], s[24:25], 0, v[156:157]
	v_lshl_add_u64 v[166:167], v[146:147], 1, v[156:157]
	v_readlane_b32 s98, v244, 9
	v_readlane_b32 s99, v244, 10
	s_nop 0
	s_add_u32 s98, s98, 0x8600000
	s_addc_u32 s99, s99, 0
	s_nop 1
	v_subrev_u32_e32 v240, s98, v166
	global_load_dwordx4 v[176:179], v240, s[98:99]
	global_load_dwordx4 v[180:183], v240, s[98:99] offset:256
	s_add_u32 s100, s98, 0x8000
	s_addc_u32 s101, s99, 0
	global_load_dwordx4 v[184:187], v240, s[100:101]
	global_load_dwordx4 v[188:191], v240, s[100:101] offset:256
	s_add_u32 s100, s98, 0x10000
	s_addc_u32 s101, s99, 0
	global_load_dwordx4 v[196:199], v240, s[100:101]
	global_load_dwordx4 v[200:203], v240, s[100:101] offset:256
	s_add_u32 s100, s98, 0x18000
	s_addc_u32 s101, s99, 0
	global_load_dwordx4 v[204:207], v240, s[100:101]
	global_load_dwordx4 v[208:211], v240, s[100:101] offset:256
	s_add_u32 s100, s98, 0x40000
	s_addc_u32 s101, s99, 0
	global_load_dwordx4 v[212:215], v240, s[100:101]
	global_load_dwordx4 v[216:219], v240, s[100:101] offset:256
	s_add_u32 s100, s98, 0x48000
	s_addc_u32 s101, s99, 0
	global_load_dwordx4 v[220:223], v240, s[100:101]
	global_load_dwordx4 v[224:227], v240, s[100:101] offset:256
	s_add_u32 s100, s98, 0x50000
	s_addc_u32 s101, s99, 0
	global_load_dwordx4 v[228:231], v240, s[100:101]
	global_load_dwordx4 v[232:235], v240, s[100:101] offset:256
	s_add_u32 s100, s98, 0x58000
	s_addc_u32 s101, s99, 0
	global_load_dwordx4 v[236:239], v240, s[100:101]
	global_load_dwordx4 v[248:251], v240, s[100:101] offset:256
	v_and_b32_e32 v157, 64, v155
	v_xor_b32_e32 v156, 16, v155
	v_add_u32_e32 v157, 64, v157
	v_cmp_lt_i32_e32 vcc, v156, v157
	s_waitcnt vmcnt(14)
	v_and_b32_e32 v169, 0xffff0000, v176
	v_cndmask_b32_e32 v156, v155, v156, vcc
	v_cmp_lt_i32_e32 vcc, v168, v157
	v_lshlrev_b32_e32 v170, 16, v178
	v_and_b32_e32 v171, 0xffff0000, v178
	v_cndmask_b32_e32 v157, v155, v168, vcc
	v_lshlrev_b32_e32 v168, 16, v176
	v_lshlrev_b32_e32 v158, 16, v177
	v_and_b32_e32 v159, 0xffff0000, v177
	v_lshlrev_b32_e32 v160, 16, v179
	v_and_b32_e32 v161, 0xffff0000, v179
	v_lshlrev_b32_e32 v172, 16, v180
	v_and_b32_e32 v173, 0xffff0000, v180
	v_lshlrev_b32_e32 v162, 16, v181
	v_and_b32_e32 v163, 0xffff0000, v181
	v_lshlrev_b32_e32 v174, 16, v182
	v_and_b32_e32 v175, 0xffff0000, v182
	v_lshlrev_b32_e32 v164, 16, v183
	v_and_b32_e32 v165, 0xffff0000, v183
	v_pk_fma_f32 v[128:129], v[128:129], 0.5, v[158:159] op_sel_hi:[1,0,1]
	v_pk_fma_f32 v[126:127], v[126:127], 0.5, v[168:169] op_sel_hi:[1,0,1]
	v_pk_fma_f32 v[124:125], v[124:125], 0.5, v[160:161] op_sel_hi:[1,0,1]
	v_pk_fma_f32 v[122:123], v[122:123], 0.5, v[170:171] op_sel_hi:[1,0,1]
	v_pk_fma_f32 v[120:121], v[120:121], 0.5, v[162:163] op_sel_hi:[1,0,1]
	v_pk_fma_f32 v[118:119], v[118:119], 0.5, v[172:173] op_sel_hi:[1,0,1]
	v_pk_fma_f32 v[158:159], v[116:117], 0.5, v[164:165] op_sel_hi:[1,0,1]
	v_pk_fma_f32 v[160:161], v[114:115], 0.5, v[174:175] op_sel_hi:[1,0,1]
	v_cvt_pk_bf16_f32 v114, v126, v127
	v_cvt_pk_bf16_f32 v115, v128, v129
	v_mul_f32_e32 v116, v127, v127
	v_mul_f32_e32 v117, v129, v129
	v_mul_f32_e32 v127, v123, v123
	v_mul_f32_e32 v129, v125, v125
	v_mul_f32_e32 v162, v119, v119
	v_mul_f32_e32 v163, v121, v121
	v_mul_f32_e32 v164, v161, v161
	v_mul_f32_e32 v165, v159, v159
	v_fmac_f32_e32 v116, v126, v126
	v_fmac_f32_e32 v117, v128, v128
	v_fmac_f32_e32 v127, v122, v122
	v_fmac_f32_e32 v129, v124, v124
	v_fmac_f32_e32 v162, v118, v118
	v_fmac_f32_e32 v163, v120, v120
	v_fmac_f32_e32 v164, v160, v160
	v_fmac_f32_e32 v165, v158, v158
	v_add_f32_e32 v116, v116, v117
	v_add_f32_e32 v117, v127, v129
	v_add_f32_e32 v126, v162, v163
	v_add_f32_e32 v127, v164, v165
	v_add_f32_e32 v116, v116, v117
	v_add_f32_e32 v117, v126, v127
	v_lshlrev_b32_e32 v156, 2, v156
	v_add_f32_e32 v126, v116, v117
	ds_bpermute_b32 v127, v156, v126
	v_cvt_pk_bf16_f32 v116, v122, v123
	v_cvt_pk_bf16_f32 v117, v124, v125
	global_store_dwordx4 v[166:167], v[114:117], off
	v_cvt_pk_bf16_f32 v118, v118, v119
	v_cvt_pk_bf16_f32 v119, v120, v121
	s_waitcnt lgkmcnt(0)
	v_add_f32_e32 v114, v126, v127
	v_lshlrev_b32_e32 v116, 2, v157
	ds_bpermute_b32 v115, v116, v114
	v_cvt_pk_bf16_f32 v120, v160, v161
	v_cvt_pk_bf16_f32 v121, v158, v159
	global_store_dwordx4 v[166:167], v[118:121], off offset:256
	s_and_saveexec_b64 s[36:37], s[0:1]
	s_cbranch_execz .LBB0_1043
	s_waitcnt lgkmcnt(0)
	v_add_f32_e32 v114, v114, v115
	v_fma_f32 v114, v114, s51, 0.5
	v_cvt_u32_f32_e32 v117, v114
	v_lshl_add_u64 v[114:115], v[148:149], 2, s[10:11]
	global_atomic_add v[114:115], v117, off
; DI unsigned pk2(float lo, float hi) { f32x2 v = {lo, hi}; return __builtin_bit_cast(unsigned, __builtin_convertvector(v, bf16v2)); }
; DI void ssq_add(float* ssq, int row, float s) { atomicAdd((unsigned*)ssq + row, (unsigned)(s * 1024.f + 0.5f)); }
;     __device__ __forceinline__ void operator()(const f32x4 (&acc)[2][2][4][2], const Unit& u, int wr, int wc, int fr, int fq, const Pre&) const {
;     ...
;             for (int m = 0; m < 4; ++m) {
;                 const int row = row0 + ai * HALF + m * 16; const size_t off = (size_t)row * DM + col0; float s = 0.f;
; #pragma unroll
;                 for (int bj = 0; bj < 2; ++bj) {
;                     f32x4 b0, b1;
;                     if (BASE_F32) { const float* bp = (const float*)base + off + bj * HALF; b0 = *(const f32x4*)bp; b1 = *(const f32x4*)(bp + 4); }
;                     else { const u32x4 w = *(const u32x4*)((const bf16_t*)base + off + bj * HALF); b0 = (f32x4){bflo(w.x), bfhi(w.x), bflo(w.y), bfhi(w.y)}; b1 = (f32x4){bflo(w.z), bfhi(w.z), bflo(w.w), bfhi(w.w)}; }
;                     const f32x4 o0 = b0 + acc[ai][bj][m][0] * alpha, o1 = b1 + acc[ai][bj][m][1] * alpha;
;                     if (OUT_F32) { float* op = (float*)out + off + bj * HALF; *(f32x4*)op = o0; *(f32x4*)(op + 4) = o1; }
;                     else { u32x4 w; w.x = pk2(o0[0], o0[1]); w.y = pk2(o0[2], o0[3]); w.z = pk2(o1[0], o1[1]); w.w = pk2(o1[2], o1[3]); *(u32x4*)((bf16_t*)out + off + bj * HALF) = w; }
;                     s += ((o0[0] * o0[0] + o0[1] * o0[1]) + (o0[2] * o0[2] + o0[3] * o0[3])) + ((o1[0] * o1[0] + o1[1] * o1[1]) + (o1[2] * o1[2] + o1[3] * o1[3]));
;                 }
;                 if (ssq) { s += __shfl_xor(s, 16); s += __shfl_xor(s, 32); if (fq == 0) ssq_add(ssq, row, s); }
.LBB0_1043:
	s_or_b64 exec, exec, s[36:37]
	v_or_b32_e32 v114, 16, v148
	s_waitcnt lgkmcnt(0)
	v_ashrrev_i32_e32 v115, 31, v114
	v_readlane_b32 s24, v244, 63
	v_lshlrev_b64 v[118:119], 11, v[114:115]
	v_readlane_b32 s25, v243, 0
	s_nop 1
	v_lshl_add_u64 v[118:119], s[24:25], 0, v[118:119]
	v_lshl_add_u64 v[126:127], v[146:147], 1, v[118:119]
	s_waitcnt vmcnt(16)
	v_lshlrev_b32_e32 v128, 16, v184
	v_and_b32_e32 v129, 0xffff0000, v184
	v_lshlrev_b32_e32 v118, 16, v185
	v_and_b32_e32 v119, 0xffff0000, v185
	v_lshlrev_b32_e32 v158, 16, v186
	v_and_b32_e32 v159, 0xffff0000, v186
	v_lshlrev_b32_e32 v120, 16, v187
	v_and_b32_e32 v121, 0xffff0000, v187
	s_waitcnt vmcnt(15)
	v_lshlrev_b32_e32 v160, 16, v188
	v_and_b32_e32 v161, 0xffff0000, v188
	v_lshlrev_b32_e32 v122, 16, v189
	v_and_b32_e32 v123, 0xffff0000, v189
	v_lshlrev_b32_e32 v162, 16, v190
	v_and_b32_e32 v163, 0xffff0000, v190
	v_lshlrev_b32_e32 v124, 16, v191
	v_and_b32_e32 v125, 0xffff0000, v191
	v_pk_fma_f32 v[112:113], v[112:113], 0.5, v[118:119] op_sel_hi:[1,0,1]
	v_pk_fma_f32 v[110:111], v[110:111], 0.5, v[128:129] op_sel_hi:[1,0,1]
	v_pk_fma_f32 v[108:109], v[108:109], 0.5, v[120:121] op_sel_hi:[1,0,1]
	v_pk_fma_f32 v[106:107], v[106:107], 0.5, v[158:159] op_sel_hi:[1,0,1]
	v_pk_fma_f32 v[104:105], v[104:105], 0.5, v[122:123] op_sel_hi:[1,0,1]
	v_pk_fma_f32 v[102:103], v[102:103], 0.5, v[160:161] op_sel_hi:[1,0,1]
	v_pk_fma_f32 v[118:119], v[100:101], 0.5, v[124:125] op_sel_hi:[1,0,1]
	v_pk_fma_f32 v[120:121], v[98:99], 0.5, v[162:163] op_sel_hi:[1,0,1]
	v_cvt_pk_bf16_f32 v98, v110, v111
	v_cvt_pk_bf16_f32 v99, v112, v113
	v_mul_f32_e32 v100, v111, v111
	v_mul_f32_e32 v101, v113, v113
	v_mul_f32_e32 v111, v107, v107
	v_mul_f32_e32 v113, v109, v109
	v_mul_f32_e32 v117, v103, v103
	v_mul_f32_e32 v122, v105, v105
	v_mul_f32_e32 v123, v121, v121
	v_mul_f32_e32 v124, v119, v119
	v_fmac_f32_e32 v100, v110, v110
	v_fmac_f32_e32 v101, v112, v112
	v_fmac_f32_e32 v111, v106, v106
	v_fmac_f32_e32 v113, v108, v108
	v_fmac_f32_e32 v117, v102, v102
	v_fmac_f32_e32 v122, v104, v104
	v_fmac_f32_e32 v123, v120, v120
	v_fmac_f32_e32 v124, v118, v118
	v_add_f32_e32 v100, v100, v101
	v_add_f32_e32 v101, v111, v113
	v_add_f32_e32 v110, v117, v122
	v_add_f32_e32 v111, v123, v124
	v_add_f32_e32 v100, v100, v101
	v_add_f32_e32 v101, v110, v111
	v_add_f32_e32 v110, v100, v101
	ds_bpermute_b32 v111, v156, v110
	v_cvt_pk_bf16_f32 v100, v106, v107
	v_cvt_pk_bf16_f32 v101, v108, v109
	global_store_dwordx4 v[126:127], v[98:101], off
	s_waitcnt lgkmcnt(0)
	s_nop 0
	v_add_f32_e32 v98, v110, v111
	ds_bpermute_b32 v99, v116, v98
	v_cvt_pk_bf16_f32 v100, v102, v103
	v_cvt_pk_bf16_f32 v101, v104, v105
	v_cvt_pk_bf16_f32 v102, v120, v121
	v_cvt_pk_bf16_f32 v103, v118, v119
	global_store_dwordx4 v[126:127], v[100:103], off offset:256
	s_and_saveexec_b64 s[36:37], s[0:1]
	s_cbranch_execz .LBB0_1045
	s_waitcnt lgkmcnt(0)
	v_add_f32_e32 v98, v98, v99
	v_fma_f32 v98, v98, s51, 0.5
	v_cvt_u32_f32_e32 v100, v98
	v_lshl_add_u64 v[98:99], v[114:115], 2, s[10:11]
	global_atomic_add v[98:99], v100, off
.LBB0_1045:
	s_or_b64 exec, exec, s[36:37]
	v_or_b32_e32 v98, 32, v148
	s_waitcnt lgkmcnt(0)
	v_ashrrev_i32_e32 v99, 31, v98
	v_readlane_b32 s24, v244, 63
	v_lshlrev_b64 v[100:101], 11, v[98:99]
	v_readlane_b32 s25, v243, 0
	s_nop 1
	v_lshl_add_u64 v[100:101], s[24:25], 0, v[100:101]
	v_lshl_add_u64 v[108:109], v[146:147], 1, v[100:101]
	s_waitcnt vmcnt(17)
	v_lshlrev_b32_e32 v110, 16, v196
	v_and_b32_e32 v111, 0xffff0000, v196
	v_lshlrev_b32_e32 v100, 16, v197
	v_and_b32_e32 v101, 0xffff0000, v197
	v_lshlrev_b32_e32 v112, 16, v198
	v_and_b32_e32 v113, 0xffff0000, v198
	v_lshlrev_b32_e32 v102, 16, v199
	v_and_b32_e32 v103, 0xffff0000, v199
	s_waitcnt vmcnt(16)
	v_lshlrev_b32_e32 v114, 16, v200
	v_and_b32_e32 v115, 0xffff0000, v200
	v_lshlrev_b32_e32 v104, 16, v201
	v_and_b32_e32 v105, 0xffff0000, v201
	v_lshlrev_b32_e32 v118, 16, v202
	v_and_b32_e32 v119, 0xffff0000, v202
	v_lshlrev_b32_e32 v106, 16, v203
	v_and_b32_e32 v107, 0xffff0000, v203
	v_pk_fma_f32 v[96:97], v[96:97], 0.5, v[100:101] op_sel_hi:[1,0,1]
	v_pk_fma_f32 v[94:95], v[94:95], 0.5, v[110:111] op_sel_hi:[1,0,1]
	v_pk_fma_f32 v[92:93], v[92:93], 0.5, v[102:103] op_sel_hi:[1,0,1]
	v_pk_fma_f32 v[90:91], v[90:91], 0.5, v[112:113] op_sel_hi:[1,0,1]
	v_pk_fma_f32 v[88:89], v[88:89], 0.5, v[104:105] op_sel_hi:[1,0,1]
	v_pk_fma_f32 v[86:87], v[86:87], 0.5, v[114:115] op_sel_hi:[1,0,1]
	v_pk_fma_f32 v[100:101], v[84:85], 0.5, v[106:107] op_sel_hi:[1,0,1]
	v_pk_fma_f32 v[102:103], v[82:83], 0.5, v[118:119] op_sel_hi:[1,0,1]
	v_cvt_pk_bf16_f32 v82, v94, v95
	v_cvt_pk_bf16_f32 v83, v96, v97
	v_mul_f32_e32 v84, v95, v95
	v_mul_f32_e32 v85, v97, v97
	v_mul_f32_e32 v95, v91, v91
	v_mul_f32_e32 v97, v93, v93
	v_mul_f32_e32 v104, v87, v87
	v_mul_f32_e32 v105, v89, v89
	v_mul_f32_e32 v106, v103, v103
	v_mul_f32_e32 v107, v101, v101
	v_fmac_f32_e32 v84, v94, v94
	v_fmac_f32_e32 v85, v96, v96
	v_fmac_f32_e32 v95, v90, v90
	v_fmac_f32_e32 v97, v92, v92
	v_fmac_f32_e32 v104, v86, v86
	v_fmac_f32_e32 v105, v88, v88
	v_fmac_f32_e32 v106, v102, v102
	v_fmac_f32_e32 v107, v100, v100
	v_add_f32_e32 v84, v84, v85
	v_add_f32_e32 v85, v95, v97
	v_add_f32_e32 v94, v104, v105
	v_add_f32_e32 v95, v106, v107
	v_add_f32_e32 v84, v84, v85
	v_add_f32_e32 v85, v94, v95
	v_add_f32_e32 v94, v84, v85
	ds_bpermute_b32 v95, v156, v94
	v_cvt_pk_bf16_f32 v84, v90, v91
	v_cvt_pk_bf16_f32 v85, v92, v93
	global_store_dwordx4 v[108:109], v[82:85], off
	s_waitcnt lgkmcnt(0)
	s_nop 0
	v_add_f32_e32 v82, v94, v95
	ds_bpermute_b32 v83, v116, v82
	v_cvt_pk_bf16_f32 v84, v86, v87
	v_cvt_pk_bf16_f32 v85, v88, v89
	v_cvt_pk_bf16_f32 v86, v102, v103
	v_cvt_pk_bf16_f32 v87, v100, v101
	global_store_dwordx4 v[108:109], v[84:87], off offset:256
	s_and_saveexec_b64 s[36:37], s[0:1]
	s_cbranch_execz .LBB0_1047
	s_waitcnt lgkmcnt(0)
	v_add_f32_e32 v82, v82, v83
	v_fma_f32 v82, v82, s51, 0.5
	v_cvt_u32_f32_e32 v84, v82
	v_lshl_add_u64 v[82:83], v[98:99], 2, s[10:11]
	global_atomic_add v[82:83], v84, off
; DI unsigned pk2(float lo, float hi) { f32x2 v = {lo, hi}; return __builtin_bit_cast(unsigned, __builtin_convertvector(v, bf16v2)); }
; DI void ssq_add(float* ssq, int row, float s) { atomicAdd((unsigned*)ssq + row, (unsigned)(s * 1024.f + 0.5f)); }
;     __device__ __forceinline__ void operator()(const f32x4 (&acc)[2][2][4][2], const Unit& u, int wr, int wc, int fr, int fq, const Pre&) const {
;     ...
;             for (int m = 0; m < 4; ++m) {
;                 const int row = row0 + ai * HALF + m * 16; const size_t off = (size_t)row * DM + col0; float s = 0.f;
; #pragma unroll
;                 for (int bj = 0; bj < 2; ++bj) {
;                     f32x4 b0, b1;
;                     if (BASE_F32) { const float* bp = (const float*)base + off + bj * HALF; b0 = *(const f32x4*)bp; b1 = *(const f32x4*)(bp + 4); }
;                     else { const u32x4 w = *(const u32x4*)((const bf16_t*)base + off + bj * HALF); b0 = (f32x4){bflo(w.x), bfhi(w.x), bflo(w.y), bfhi(w.y)}; b1 = (f32x4){bflo(w.z), bfhi(w.z), bflo(w.w), bfhi(w.w)}; }
;                     const f32x4 o0 = b0 + acc[ai][bj][m][0] * alpha, o1 = b1 + acc[ai][bj][m][1] * alpha;
;                     if (OUT_F32) { float* op = (float*)out + off + bj * HALF; *(f32x4*)op = o0; *(f32x4*)(op + 4) = o1; }
;                     else { u32x4 w; w.x = pk2(o0[0], o0[1]); w.y = pk2(o0[2], o0[3]); w.z = pk2(o1[0], o1[1]); w.w = pk2(o1[2], o1[3]); *(u32x4*)((bf16_t*)out + off + bj * HALF) = w; }
;                     s += ((o0[0] * o0[0] + o0[1] * o0[1]) + (o0[2] * o0[2] + o0[3] * o0[3])) + ((o1[0] * o1[0] + o1[1] * o1[1]) + (o1[2] * o1[2] + o1[3] * o1[3]));
;                 }
;                 if (ssq) { s += __shfl_xor(s, 16); s += __shfl_xor(s, 32); if (fq == 0) ssq_add(ssq, row, s); }
.LBB0_1047:
	s_or_b64 exec, exec, s[36:37]
	v_or_b32_e32 v82, 48, v148
	s_waitcnt lgkmcnt(0)
	v_ashrrev_i32_e32 v83, 31, v82
	v_readlane_b32 s24, v244, 63
	v_lshlrev_b64 v[84:85], 11, v[82:83]
	v_readlane_b32 s25, v243, 0
	s_nop 1
	v_lshl_add_u64 v[84:85], s[24:25], 0, v[84:85]
	v_lshl_add_u64 v[92:93], v[146:147], 1, v[84:85]
	s_waitcnt vmcnt(18)
	v_lshlrev_b32_e32 v94, 16, v204
	v_and_b32_e32 v95, 0xffff0000, v204
	v_lshlrev_b32_e32 v84, 16, v205
	v_and_b32_e32 v85, 0xffff0000, v205
	v_lshlrev_b32_e32 v96, 16, v206
	v_and_b32_e32 v97, 0xffff0000, v206
	v_lshlrev_b32_e32 v86, 16, v207
	v_and_b32_e32 v87, 0xffff0000, v207
	s_waitcnt vmcnt(17)
	v_lshlrev_b32_e32 v98, 16, v208
	v_and_b32_e32 v99, 0xffff0000, v208
	v_lshlrev_b32_e32 v88, 16, v209
	v_and_b32_e32 v89, 0xffff0000, v209
	v_lshlrev_b32_e32 v100, 16, v210
	v_and_b32_e32 v101, 0xffff0000, v210
	v_lshlrev_b32_e32 v90, 16, v211
	v_and_b32_e32 v91, 0xffff0000, v211
	v_pk_fma_f32 v[80:81], v[80:81], 0.5, v[84:85] op_sel_hi:[1,0,1]
	v_pk_fma_f32 v[78:79], v[78:79], 0.5, v[94:95] op_sel_hi:[1,0,1]
	v_pk_fma_f32 v[76:77], v[76:77], 0.5, v[86:87] op_sel_hi:[1,0,1]
	v_pk_fma_f32 v[74:75], v[74:75], 0.5, v[96:97] op_sel_hi:[1,0,1]
	v_pk_fma_f32 v[72:73], v[72:73], 0.5, v[88:89] op_sel_hi:[1,0,1]
	v_pk_fma_f32 v[70:71], v[70:71], 0.5, v[98:99] op_sel_hi:[1,0,1]
	v_pk_fma_f32 v[84:85], v[68:69], 0.5, v[90:91] op_sel_hi:[1,0,1]
	v_pk_fma_f32 v[86:87], v[66:67], 0.5, v[100:101] op_sel_hi:[1,0,1]
	v_cvt_pk_bf16_f32 v66, v78, v79
	v_cvt_pk_bf16_f32 v67, v80, v81
	v_mul_f32_e32 v68, v79, v79
	v_mul_f32_e32 v69, v81, v81
	v_mul_f32_e32 v79, v75, v75
	v_mul_f32_e32 v81, v77, v77
	v_mul_f32_e32 v88, v71, v71
	v_mul_f32_e32 v89, v73, v73
	v_mul_f32_e32 v90, v87, v87
	v_mul_f32_e32 v91, v85, v85
	v_fmac_f32_e32 v68, v78, v78
	v_fmac_f32_e32 v69, v80, v80
	v_fmac_f32_e32 v79, v74, v74
	v_fmac_f32_e32 v81, v76, v76
	v_fmac_f32_e32 v88, v70, v70
	v_fmac_f32_e32 v89, v72, v72
	v_fmac_f32_e32 v90, v86, v86
	v_fmac_f32_e32 v91, v84, v84
	v_add_f32_e32 v68, v68, v69
	v_add_f32_e32 v69, v79, v81
	v_add_f32_e32 v78, v88, v89
	v_add_f32_e32 v79, v90, v91
	v_add_f32_e32 v68, v68, v69
	v_add_f32_e32 v69, v78, v79
	v_add_f32_e32 v78, v68, v69
	ds_bpermute_b32 v79, v156, v78
	v_cvt_pk_bf16_f32 v68, v74, v75
	v_cvt_pk_bf16_f32 v69, v76, v77
	global_store_dwordx4 v[92:93], v[66:69], off
	s_waitcnt lgkmcnt(0)
	s_nop 0
	v_add_f32_e32 v66, v78, v79
	ds_bpermute_b32 v67, v116, v66
	v_cvt_pk_bf16_f32 v68, v70, v71
	v_cvt_pk_bf16_f32 v69, v72, v73
	v_cvt_pk_bf16_f32 v70, v86, v87
	v_cvt_pk_bf16_f32 v71, v84, v85
	global_store_dwordx4 v[92:93], v[68:71], off offset:256
	s_and_saveexec_b64 s[36:37], s[0:1]
	s_cbranch_execz .LBB0_1049
	s_waitcnt lgkmcnt(0)
	v_add_f32_e32 v66, v66, v67
	v_fma_f32 v66, v66, s51, 0.5
	v_cvt_u32_f32_e32 v68, v66
	v_lshl_add_u64 v[66:67], v[82:83], 2, s[10:11]
	global_atomic_add v[66:67], v68, off
.LBB0_1049:
	s_or_b64 exec, exec, s[36:37]
	v_add_u32_e32 v66, 0x80, v148
	s_waitcnt lgkmcnt(0)
	v_ashrrev_i32_e32 v67, 31, v66
	v_readlane_b32 s24, v244, 63
	v_lshlrev_b64 v[68:69], 11, v[66:67]
	v_readlane_b32 s25, v243, 0
	s_nop 1
	v_lshl_add_u64 v[68:69], s[24:25], 0, v[68:69]
	v_lshl_add_u64 v[76:77], v[146:147], 1, v[68:69]
	s_waitcnt vmcnt(19)
	v_lshlrev_b32_e32 v78, 16, v212
	v_and_b32_e32 v79, 0xffff0000, v212
	v_lshlrev_b32_e32 v68, 16, v213
	v_and_b32_e32 v69, 0xffff0000, v213
	v_lshlrev_b32_e32 v80, 16, v214
	v_and_b32_e32 v81, 0xffff0000, v214
	v_lshlrev_b32_e32 v70, 16, v215
	v_and_b32_e32 v71, 0xffff0000, v215
	s_waitcnt vmcnt(18)
	v_lshlrev_b32_e32 v82, 16, v216
	v_and_b32_e32 v83, 0xffff0000, v216
	v_lshlrev_b32_e32 v72, 16, v217
	v_and_b32_e32 v73, 0xffff0000, v217
	v_lshlrev_b32_e32 v84, 16, v218
	v_and_b32_e32 v85, 0xffff0000, v218
	v_lshlrev_b32_e32 v74, 16, v219
	v_and_b32_e32 v75, 0xffff0000, v219
	v_pk_fma_f32 v[64:65], v[64:65], 0.5, v[68:69] op_sel_hi:[1,0,1]
	v_pk_fma_f32 v[62:63], v[62:63], 0.5, v[78:79] op_sel_hi:[1,0,1]
	v_pk_fma_f32 v[60:61], v[60:61], 0.5, v[70:71] op_sel_hi:[1,0,1]
	v_pk_fma_f32 v[58:59], v[58:59], 0.5, v[80:81] op_sel_hi:[1,0,1]
	v_pk_fma_f32 v[56:57], v[56:57], 0.5, v[72:73] op_sel_hi:[1,0,1]
	v_pk_fma_f32 v[54:55], v[54:55], 0.5, v[82:83] op_sel_hi:[1,0,1]
	v_pk_fma_f32 v[68:69], v[52:53], 0.5, v[74:75] op_sel_hi:[1,0,1]
	v_pk_fma_f32 v[70:71], v[50:51], 0.5, v[84:85] op_sel_hi:[1,0,1]
	v_cvt_pk_bf16_f32 v50, v62, v63
	v_cvt_pk_bf16_f32 v51, v64, v65
	v_mul_f32_e32 v52, v63, v63
	v_mul_f32_e32 v53, v65, v65
	v_mul_f32_e32 v63, v59, v59
	v_mul_f32_e32 v65, v61, v61
	v_mul_f32_e32 v72, v55, v55
	v_mul_f32_e32 v73, v57, v57
	v_mul_f32_e32 v74, v71, v71
	v_mul_f32_e32 v75, v69, v69
	v_fmac_f32_e32 v52, v62, v62
	v_fmac_f32_e32 v53, v64, v64
	v_fmac_f32_e32 v63, v58, v58
	v_fmac_f32_e32 v65, v60, v60
	v_fmac_f32_e32 v72, v54, v54
	v_fmac_f32_e32 v73, v56, v56
	v_fmac_f32_e32 v74, v70, v70
	v_fmac_f32_e32 v75, v68, v68
	v_add_f32_e32 v52, v52, v53
	v_add_f32_e32 v53, v63, v65
	v_add_f32_e32 v62, v72, v73
	v_add_f32_e32 v63, v74, v75
	v_add_f32_e32 v52, v52, v53
	v_add_f32_e32 v53, v62, v63
	v_add_f32_e32 v62, v52, v53
	ds_bpermute_b32 v63, v156, v62
	v_cvt_pk_bf16_f32 v52, v58, v59
	v_cvt_pk_bf16_f32 v53, v60, v61
	global_store_dwordx4 v[76:77], v[50:53], off
	s_waitcnt lgkmcnt(0)
	s_nop 0
	v_add_f32_e32 v50, v62, v63
	ds_bpermute_b32 v51, v116, v50
	v_cvt_pk_bf16_f32 v52, v54, v55
	v_cvt_pk_bf16_f32 v53, v56, v57
	v_cvt_pk_bf16_f32 v54, v70, v71
	v_cvt_pk_bf16_f32 v55, v68, v69
	global_store_dwordx4 v[76:77], v[52:55], off offset:256
	s_and_saveexec_b64 s[36:37], s[0:1]
	s_cbranch_execz .LBB0_1051
	s_waitcnt lgkmcnt(0)
	v_add_f32_e32 v50, v50, v51
	v_fma_f32 v50, v50, s51, 0.5
	v_cvt_u32_f32_e32 v52, v50
	v_lshl_add_u64 v[50:51], v[66:67], 2, s[10:11]
	global_atomic_add v[50:51], v52, off
; DI unsigned pk2(float lo, float hi) { f32x2 v = {lo, hi}; return __builtin_bit_cast(unsigned, __builtin_convertvector(v, bf16v2)); }
; DI void ssq_add(float* ssq, int row, float s) { atomicAdd((unsigned*)ssq + row, (unsigned)(s * 1024.f + 0.5f)); }
;     __device__ __forceinline__ void operator()(const f32x4 (&acc)[2][2][4][2], const Unit& u, int wr, int wc, int fr, int fq, const Pre&) const {
;     ...
;             for (int m = 0; m < 4; ++m) {
;                 const int row = row0 + ai * HALF + m * 16; const size_t off = (size_t)row * DM + col0; float s = 0.f;
; #pragma unroll
;                 for (int bj = 0; bj < 2; ++bj) {
;                     f32x4 b0, b1;
;                     if (BASE_F32) { const float* bp = (const float*)base + off + bj * HALF; b0 = *(const f32x4*)bp; b1 = *(const f32x4*)(bp + 4); }
;                     else { const u32x4 w = *(const u32x4*)((const bf16_t*)base + off + bj * HALF); b0 = (f32x4){bflo(w.x), bfhi(w.x), bflo(w.y), bfhi(w.y)}; b1 = (f32x4){bflo(w.z), bfhi(w.z), bflo(w.w), bfhi(w.w)}; }
;                     const f32x4 o0 = b0 + acc[ai][bj][m][0] * alpha, o1 = b1 + acc[ai][bj][m][1] * alpha;
;                     if (OUT_F32) { float* op = (float*)out + off + bj * HALF; *(f32x4*)op = o0; *(f32x4*)(op + 4) = o1; }
;                     else { u32x4 w; w.x = pk2(o0[0], o0[1]); w.y = pk2(o0[2], o0[3]); w.z = pk2(o1[0], o1[1]); w.w = pk2(o1[2], o1[3]); *(u32x4*)((bf16_t*)out + off + bj * HALF) = w; }
;                     s += ((o0[0] * o0[0] + o0[1] * o0[1]) + (o0[2] * o0[2] + o0[3] * o0[3])) + ((o1[0] * o1[0] + o1[1] * o1[1]) + (o1[2] * o1[2] + o1[3] * o1[3]));
;                 }
;                 if (ssq) { s += __shfl_xor(s, 16); s += __shfl_xor(s, 32); if (fq == 0) ssq_add(ssq, row, s); }
.LBB0_1051:
	s_or_b64 exec, exec, s[36:37]
	v_add_u32_e32 v50, 0x90, v148
	s_waitcnt lgkmcnt(0)
	v_ashrrev_i32_e32 v51, 31, v50
	v_readlane_b32 s24, v244, 63
	v_lshlrev_b64 v[52:53], 11, v[50:51]
	v_readlane_b32 s25, v243, 0
	s_nop 1
	v_lshl_add_u64 v[52:53], s[24:25], 0, v[52:53]
	v_lshl_add_u64 v[60:61], v[146:147], 1, v[52:53]
	s_waitcnt vmcnt(20)
	v_lshlrev_b32_e32 v62, 16, v220
	v_and_b32_e32 v63, 0xffff0000, v220
	v_lshlrev_b32_e32 v52, 16, v221
	v_and_b32_e32 v53, 0xffff0000, v221
	v_lshlrev_b32_e32 v64, 16, v222
	v_and_b32_e32 v65, 0xffff0000, v222
	v_lshlrev_b32_e32 v54, 16, v223
	v_and_b32_e32 v55, 0xffff0000, v223
	s_waitcnt vmcnt(19)
	v_lshlrev_b32_e32 v66, 16, v224
	v_and_b32_e32 v67, 0xffff0000, v224
	v_lshlrev_b32_e32 v56, 16, v225
	v_and_b32_e32 v57, 0xffff0000, v225
	v_lshlrev_b32_e32 v68, 16, v226
	v_and_b32_e32 v69, 0xffff0000, v226
	v_lshlrev_b32_e32 v58, 16, v227
	v_and_b32_e32 v59, 0xffff0000, v227
	v_pk_fma_f32 v[48:49], v[48:49], 0.5, v[52:53] op_sel_hi:[1,0,1]
	v_pk_fma_f32 v[46:47], v[46:47], 0.5, v[62:63] op_sel_hi:[1,0,1]
	v_pk_fma_f32 v[44:45], v[44:45], 0.5, v[54:55] op_sel_hi:[1,0,1]
	v_pk_fma_f32 v[42:43], v[42:43], 0.5, v[64:65] op_sel_hi:[1,0,1]
	v_pk_fma_f32 v[40:41], v[40:41], 0.5, v[56:57] op_sel_hi:[1,0,1]
	v_pk_fma_f32 v[38:39], v[38:39], 0.5, v[66:67] op_sel_hi:[1,0,1]
	v_pk_fma_f32 v[52:53], v[36:37], 0.5, v[58:59] op_sel_hi:[1,0,1]
	v_pk_fma_f32 v[54:55], v[34:35], 0.5, v[68:69] op_sel_hi:[1,0,1]
	v_cvt_pk_bf16_f32 v34, v46, v47
	v_cvt_pk_bf16_f32 v35, v48, v49
	v_mul_f32_e32 v36, v47, v47
	v_mul_f32_e32 v37, v49, v49
	v_mul_f32_e32 v47, v43, v43
	v_mul_f32_e32 v49, v45, v45
	v_mul_f32_e32 v56, v39, v39
	v_mul_f32_e32 v57, v41, v41
	v_mul_f32_e32 v58, v55, v55
	v_mul_f32_e32 v59, v53, v53
	v_fmac_f32_e32 v36, v46, v46
	v_fmac_f32_e32 v37, v48, v48
	v_fmac_f32_e32 v47, v42, v42
	v_fmac_f32_e32 v49, v44, v44
	v_fmac_f32_e32 v56, v38, v38
	v_fmac_f32_e32 v57, v40, v40
	v_fmac_f32_e32 v58, v54, v54
	v_fmac_f32_e32 v59, v52, v52
	v_add_f32_e32 v36, v36, v37
	v_add_f32_e32 v37, v47, v49
	v_add_f32_e32 v46, v56, v57
	v_add_f32_e32 v47, v58, v59
	v_add_f32_e32 v36, v36, v37
	v_add_f32_e32 v37, v46, v47
	v_add_f32_e32 v46, v36, v37
	ds_bpermute_b32 v47, v156, v46
	v_cvt_pk_bf16_f32 v36, v42, v43
	v_cvt_pk_bf16_f32 v37, v44, v45
	global_store_dwordx4 v[60:61], v[34:37], off
	s_waitcnt lgkmcnt(0)
	s_nop 0
	v_add_f32_e32 v34, v46, v47
	ds_bpermute_b32 v35, v116, v34
	v_cvt_pk_bf16_f32 v36, v38, v39
	v_cvt_pk_bf16_f32 v37, v40, v41
	v_cvt_pk_bf16_f32 v38, v54, v55
	v_cvt_pk_bf16_f32 v39, v52, v53
	global_store_dwordx4 v[60:61], v[36:39], off offset:256
	s_and_saveexec_b64 s[36:37], s[0:1]
	s_cbranch_execz .LBB0_1053
	s_waitcnt lgkmcnt(0)
	v_add_f32_e32 v34, v34, v35
	v_fma_f32 v34, v34, s51, 0.5
	v_cvt_u32_f32_e32 v36, v34
	v_lshl_add_u64 v[34:35], v[50:51], 2, s[10:11]
	global_atomic_add v[34:35], v36, off
; DI unsigned pk2(float lo, float hi) { f32x2 v = {lo, hi}; return __builtin_bit_cast(unsigned, __builtin_convertvector(v, bf16v2)); }
; DI void ssq_add(float* ssq, int row, float s) { atomicAdd((unsigned*)ssq + row, (unsigned)(s * 1024.f + 0.5f)); }
;     __device__ __forceinline__ void operator()(const f32x4 (&acc)[2][2][4][2], const Unit& u, int wr, int wc, int fr, int fq, const Pre&) const {
;     ...
;             for (int m = 0; m < 4; ++m) {
;                 const int row = row0 + ai * HALF + m * 16; const size_t off = (size_t)row * DM + col0; float s = 0.f;
; #pragma unroll
;                 for (int bj = 0; bj < 2; ++bj) {
;                     f32x4 b0, b1;
;                     if (BASE_F32) { const float* bp = (const float*)base + off + bj * HALF; b0 = *(const f32x4*)bp; b1 = *(const f32x4*)(bp + 4); }
;                     else { const u32x4 w = *(const u32x4*)((const bf16_t*)base + off + bj * HALF); b0 = (f32x4){bflo(w.x), bfhi(w.x), bflo(w.y), bfhi(w.y)}; b1 = (f32x4){bflo(w.z), bfhi(w.z), bflo(w.w), bfhi(w.w)}; }
;                     const f32x4 o0 = b0 + acc[ai][bj][m][0] * alpha, o1 = b1 + acc[ai][bj][m][1] * alpha;
;                     if (OUT_F32) { float* op = (float*)out + off + bj * HALF; *(f32x4*)op = o0; *(f32x4*)(op + 4) = o1; }
;                     else { u32x4 w; w.x = pk2(o0[0], o0[1]); w.y = pk2(o0[2], o0[3]); w.z = pk2(o1[0], o1[1]); w.w = pk2(o1[2], o1[3]); *(u32x4*)((bf16_t*)out + off + bj * HALF) = w; }
;                     s += ((o0[0] * o0[0] + o0[1] * o0[1]) + (o0[2] * o0[2] + o0[3] * o0[3])) + ((o1[0] * o1[0] + o1[1] * o1[1]) + (o1[2] * o1[2] + o1[3] * o1[3]));
;                 }
;                 if (ssq) { s += __shfl_xor(s, 16); s += __shfl_xor(s, 32); if (fq == 0) ssq_add(ssq, row, s); }
.LBB0_1053:
	s_or_b64 exec, exec, s[36:37]
	v_add_u32_e32 v34, 0xa0, v148
	s_waitcnt lgkmcnt(0)
	v_ashrrev_i32_e32 v35, 31, v34
	v_readlane_b32 s24, v244, 63
	v_lshlrev_b64 v[36:37], 11, v[34:35]
	v_readlane_b32 s25, v243, 0
	s_nop 1
	v_lshl_add_u64 v[36:37], s[24:25], 0, v[36:37]
	v_lshl_add_u64 v[44:45], v[146:147], 1, v[36:37]
	s_waitcnt vmcnt(21)
	v_lshlrev_b32_e32 v46, 16, v228
	v_and_b32_e32 v47, 0xffff0000, v228
	v_lshlrev_b32_e32 v36, 16, v229
	v_and_b32_e32 v37, 0xffff0000, v229
	v_lshlrev_b32_e32 v48, 16, v230
	v_and_b32_e32 v49, 0xffff0000, v230
	v_lshlrev_b32_e32 v38, 16, v231
	v_and_b32_e32 v39, 0xffff0000, v231
	s_waitcnt vmcnt(20)
	v_lshlrev_b32_e32 v50, 16, v232
	v_and_b32_e32 v51, 0xffff0000, v232
	v_lshlrev_b32_e32 v40, 16, v233
	v_and_b32_e32 v41, 0xffff0000, v233
	v_lshlrev_b32_e32 v52, 16, v234
	v_and_b32_e32 v53, 0xffff0000, v234
	v_lshlrev_b32_e32 v42, 16, v235
	v_and_b32_e32 v43, 0xffff0000, v235
	v_pk_fma_f32 v[32:33], v[32:33], 0.5, v[36:37] op_sel_hi:[1,0,1]
	v_pk_fma_f32 v[30:31], v[30:31], 0.5, v[46:47] op_sel_hi:[1,0,1]
	v_pk_fma_f32 v[28:29], v[28:29], 0.5, v[38:39] op_sel_hi:[1,0,1]
	v_pk_fma_f32 v[26:27], v[26:27], 0.5, v[48:49] op_sel_hi:[1,0,1]
	v_pk_fma_f32 v[24:25], v[24:25], 0.5, v[40:41] op_sel_hi:[1,0,1]
	v_pk_fma_f32 v[22:23], v[22:23], 0.5, v[50:51] op_sel_hi:[1,0,1]
	v_pk_fma_f32 v[36:37], v[20:21], 0.5, v[42:43] op_sel_hi:[1,0,1]
	v_pk_fma_f32 v[38:39], v[18:19], 0.5, v[52:53] op_sel_hi:[1,0,1]
	v_cvt_pk_bf16_f32 v18, v30, v31
	v_cvt_pk_bf16_f32 v19, v32, v33
	v_mul_f32_e32 v20, v31, v31
	v_mul_f32_e32 v21, v33, v33
	v_mul_f32_e32 v31, v27, v27
	v_mul_f32_e32 v33, v29, v29
	v_mul_f32_e32 v40, v23, v23
	v_mul_f32_e32 v41, v25, v25
	v_mul_f32_e32 v42, v39, v39
	v_mul_f32_e32 v43, v37, v37
	v_fmac_f32_e32 v20, v30, v30
	v_fmac_f32_e32 v21, v32, v32
	v_fmac_f32_e32 v31, v26, v26
	v_fmac_f32_e32 v33, v28, v28
	v_fmac_f32_e32 v40, v22, v22
	v_fmac_f32_e32 v41, v24, v24
	v_fmac_f32_e32 v42, v38, v38
	v_fmac_f32_e32 v43, v36, v36
	v_add_f32_e32 v20, v20, v21
	v_add_f32_e32 v21, v31, v33
	v_add_f32_e32 v30, v40, v41
	v_add_f32_e32 v31, v42, v43
	v_add_f32_e32 v20, v20, v21
	v_add_f32_e32 v21, v30, v31
	v_add_f32_e32 v30, v20, v21
	ds_bpermute_b32 v31, v156, v30
	v_cvt_pk_bf16_f32 v20, v26, v27
	v_cvt_pk_bf16_f32 v21, v28, v29
	global_store_dwordx4 v[44:45], v[18:21], off
	s_waitcnt lgkmcnt(0)
	s_nop 0
	v_add_f32_e32 v18, v30, v31
	ds_bpermute_b32 v19, v116, v18
	v_cvt_pk_bf16_f32 v20, v22, v23
	v_cvt_pk_bf16_f32 v21, v24, v25
	v_cvt_pk_bf16_f32 v22, v38, v39
	v_cvt_pk_bf16_f32 v23, v36, v37
	global_store_dwordx4 v[44:45], v[20:23], off offset:256
	s_and_saveexec_b64 s[36:37], s[0:1]
	s_cbranch_execz .LBB0_1055
	s_waitcnt lgkmcnt(0)
	v_add_f32_e32 v18, v18, v19
	v_fma_f32 v18, v18, s51, 0.5
	v_cvt_u32_f32_e32 v20, v18
	v_lshl_add_u64 v[18:19], v[34:35], 2, s[10:11]
	global_atomic_add v[18:19], v20, off
.LBB0_1055:
	s_or_b64 exec, exec, s[36:37]
	v_add_u32_e32 v18, 0xb0, v148
	s_waitcnt lgkmcnt(0)
	v_ashrrev_i32_e32 v19, 31, v18
	v_readlane_b32 s24, v244, 63
	v_lshlrev_b64 v[20:21], 11, v[18:19]
	v_readlane_b32 s25, v243, 0
	s_nop 1
	v_lshl_add_u64 v[20:21], s[24:25], 0, v[20:21]
	v_lshl_add_u64 v[28:29], v[146:147], 1, v[20:21]
	s_waitcnt vmcnt(22)
	v_lshlrev_b32_e32 v30, 16, v236
	v_and_b32_e32 v31, 0xffff0000, v236
	v_lshlrev_b32_e32 v20, 16, v237
	v_and_b32_e32 v21, 0xffff0000, v237
	v_lshlrev_b32_e32 v32, 16, v238
	v_and_b32_e32 v33, 0xffff0000, v238
	v_lshlrev_b32_e32 v22, 16, v239
	v_and_b32_e32 v23, 0xffff0000, v239
	s_waitcnt vmcnt(21)
	v_lshlrev_b32_e32 v34, 16, v248
	v_and_b32_e32 v35, 0xffff0000, v248
	v_lshlrev_b32_e32 v24, 16, v249
	v_and_b32_e32 v25, 0xffff0000, v249
	v_lshlrev_b32_e32 v36, 16, v250
	v_and_b32_e32 v37, 0xffff0000, v250
	v_lshlrev_b32_e32 v26, 16, v251
	v_and_b32_e32 v27, 0xffff0000, v251
	v_pk_fma_f32 v[16:17], v[16:17], 0.5, v[20:21] op_sel_hi:[1,0,1]
	v_pk_fma_f32 v[14:15], v[14:15], 0.5, v[30:31] op_sel_hi:[1,0,1]
	v_pk_fma_f32 v[12:13], v[12:13], 0.5, v[22:23] op_sel_hi:[1,0,1]
	v_pk_fma_f32 v[10:11], v[10:11], 0.5, v[32:33] op_sel_hi:[1,0,1]
	v_pk_fma_f32 v[8:9], v[8:9], 0.5, v[24:25] op_sel_hi:[1,0,1]
	v_pk_fma_f32 v[6:7], v[6:7], 0.5, v[34:35] op_sel_hi:[1,0,1]
	v_pk_fma_f32 v[20:21], v[4:5], 0.5, v[26:27] op_sel_hi:[1,0,1]
	v_pk_fma_f32 v[22:23], v[2:3], 0.5, v[36:37] op_sel_hi:[1,0,1]
	v_cvt_pk_bf16_f32 v2, v14, v15
	v_cvt_pk_bf16_f32 v3, v16, v17
	v_mul_f32_e32 v4, v15, v15
	v_mul_f32_e32 v5, v17, v17
	v_mul_f32_e32 v15, v11, v11
	v_mul_f32_e32 v17, v13, v13
	v_mul_f32_e32 v24, v7, v7
	v_mul_f32_e32 v25, v9, v9
	v_mul_f32_e32 v26, v23, v23
	v_mul_f32_e32 v27, v21, v21
	v_fmac_f32_e32 v4, v14, v14
	v_fmac_f32_e32 v5, v16, v16
	v_fmac_f32_e32 v15, v10, v10
	v_fmac_f32_e32 v17, v12, v12
	v_fmac_f32_e32 v24, v6, v6
	v_fmac_f32_e32 v25, v8, v8
	v_fmac_f32_e32 v26, v22, v22
	v_fmac_f32_e32 v27, v20, v20
	v_add_f32_e32 v4, v4, v5
	v_add_f32_e32 v5, v15, v17
	v_add_f32_e32 v14, v24, v25
	v_add_f32_e32 v15, v26, v27
	v_add_f32_e32 v4, v4, v5
	v_add_f32_e32 v5, v14, v15
	v_add_f32_e32 v14, v4, v5
	ds_bpermute_b32 v15, v156, v14
	v_cvt_pk_bf16_f32 v4, v10, v11
	v_cvt_pk_bf16_f32 v5, v12, v13
	global_store_dwordx4 v[28:29], v[2:5], off
	s_waitcnt lgkmcnt(0)
	s_nop 0
	v_add_f32_e32 v2, v14, v15
	ds_bpermute_b32 v3, v116, v2
	v_cvt_pk_bf16_f32 v4, v6, v7
	v_cvt_pk_bf16_f32 v5, v8, v9
	v_cvt_pk_bf16_f32 v6, v22, v23
	v_cvt_pk_bf16_f32 v7, v20, v21
	global_store_dwordx4 v[28:29], v[4:7], off offset:256
	s_and_saveexec_b64 s[36:37], s[0:1]
	s_cbranch_execz .LBB0_1057
	s_waitcnt lgkmcnt(0)
	v_add_f32_e32 v2, v2, v3
	v_fma_f32 v2, v2, s51, 0.5
	v_cvt_u32_f32_e32 v4, v2
	v_lshl_add_u64 v[2:3], v[18:19], 2, s[10:11]
	global_atomic_add v[2:3], v4, off

; DI unsigned pk2(float lo, float hi) { f32x2 v = {lo, hi}; return __builtin_bit_cast(unsigned, __builtin_convertvector(v, bf16v2)); }
; DI void ssq_add(float* ssq, int row, float s) { atomicAdd((unsigned*)ssq + row, (unsigned)(s * 1024.f + 0.5f)); }
;     __device__ __forceinline__ void operator()(const f32x4 (&acc)[2][2][4][2], const Unit& u, int wr, int wc, int fr, int fq, const Pre&) const {
;         const int row0 = u.pm * BM + wr * 64 + fr, col0 = u.pn * BM + wc * 32 + 8 * fq;
; #pragma unroll
;         for (int ai = 0; ai < 2; ++ai)
; #pragma unroll
;             for (int m = 0; m < 4; ++m) {
;                 const int row = row0 + ai * HALF + m * 16; const size_t off = (size_t)row * DM + col0; float s = 0.f;
; #pragma unroll
;                 for (int bj = 0; bj < 2; ++bj) {
;                     f32x4 b0, b1;
;                     if (BASE_F32) { const float* bp = (const float*)base + off + bj * HALF; b0 = *(const f32x4*)bp; b1 = *(const f32x4*)(bp + 4); }
;                     else { const u32x4 w = *(const u32x4*)((const bf16_t*)base + off + bj * HALF); b0 = (f32x4){bflo(w.x), bfhi(w.x), bflo(w.y), bfhi(w.y)}; b1 = (f32x4){bflo(w.z), bfhi(w.z), bflo(w.w), bfhi(w.w)}; }
;                     const f32x4 o0 = b0 + acc[ai][bj][m][0] * alpha, o1 = b1 + acc[ai][bj][m][1] * alpha;
;                     if (OUT_F32) { float* op = (float*)out + off + bj * HALF; *(f32x4*)op = o0; *(f32x4*)(op + 4) = o1; }
;                     else { u32x4 w; w.x = pk2(o0[0], o0[1]); w.y = pk2(o0[2], o0[3]); w.z = pk2(o1[0], o1[1]); w.w = pk2(o1[2], o1[3]); *(u32x4*)((bf16_t*)out + off + bj * HALF) = w; }
;                     s += ((o0[0] * o0[0] + o0[1] * o0[1]) + (o0[2] * o0[2] + o0[3] * o0[3])) + ((o1[0] * o1[0] + o1[1] * o1[1]) + (o1[2] * o1[2] + o1[3] * o1[3]));
;                 }
;                 if (ssq) { s += __shfl_xor(s, 16); s += __shfl_xor(s, 32); if (fq == 0) ssq_add(ssq, row, s); }
.LBB0_1951:
	v_lshl_add_u32 v148, s26, 8, v1
	v_ashrrev_i32_e32 v149, 31, v148
	v_readlane_b32 s26, v244, 63
	v_lshl_or_b32 v146, s34, 8, v151
	v_lshlrev_b64 v[156:157], 11, v[148:149]
	v_readlane_b32 s27, v243, 0
	v_ashrrev_i32_e32 v147, 31, v146
	v_xor_b32_e32 v168, 32, v155
	v_lshl_add_u64 v[156:157], s[26:27], 0, v[156:157]
	v_lshl_add_u64 v[166:167], v[146:147], 1, v[156:157]
	v_readlane_b32 s98, v244, 9
	v_readlane_b32 s99, v244, 10
	s_nop 0
	s_add_u32 s98, s98, 0x8600000
	s_addc_u32 s99, s99, 0
	s_nop 1
	v_subrev_u32_e32 v240, s98, v166
	global_load_dwordx4 v[176:179], v240, s[98:99]
	global_load_dwordx4 v[180:183], v240, s[98:99] offset:256
	s_add_u32 s100, s98, 0x8000
	s_addc_u32 s101, s99, 0
	global_load_dwordx4 v[184:187], v240, s[100:101]
	global_load_dwordx4 v[188:191], v240, s[100:101] offset:256
	s_add_u32 s100, s98, 0x10000
	s_addc_u32 s101, s99, 0
	global_load_dwordx4 v[196:199], v240, s[100:101]
	global_load_dwordx4 v[200:203], v240, s[100:101] offset:256
	s_add_u32 s100, s98, 0x18000
	s_addc_u32 s101, s99, 0
	global_load_dwordx4 v[204:207], v240, s[100:101]
	global_load_dwordx4 v[208:211], v240, s[100:101] offset:256
	s_add_u32 s100, s98, 0x40000
	s_addc_u32 s101, s99, 0
	global_load_dwordx4 v[212:215], v240, s[100:101]
	global_load_dwordx4 v[216:219], v240, s[100:101] offset:256
	s_add_u32 s100, s98, 0x48000
	s_addc_u32 s101, s99, 0
	global_load_dwordx4 v[220:223], v240, s[100:101]
	global_load_dwordx4 v[224:227], v240, s[100:101] offset:256
	s_add_u32 s100, s98, 0x50000
	s_addc_u32 s101, s99, 0
	global_load_dwordx4 v[228:231], v240, s[100:101]
	global_load_dwordx4 v[232:235], v240, s[100:101] offset:256
	s_add_u32 s100, s98, 0x58000
	s_addc_u32 s101, s99, 0
	global_load_dwordx4 v[236:239], v240, s[100:101]
	global_load_dwordx4 v[248:251], v240, s[100:101] offset:256
	v_and_b32_e32 v157, 64, v155
	v_xor_b32_e32 v156, 16, v155
	v_add_u32_e32 v157, 64, v157
	v_cmp_lt_i32_e32 vcc, v156, v157
	s_waitcnt vmcnt(14)
	v_and_b32_e32 v169, 0xffff0000, v176
	v_cndmask_b32_e32 v156, v155, v156, vcc
	v_cmp_lt_i32_e32 vcc, v168, v157
	v_lshlrev_b32_e32 v170, 16, v178
	v_and_b32_e32 v171, 0xffff0000, v178
	v_cndmask_b32_e32 v157, v155, v168, vcc
	v_lshlrev_b32_e32 v168, 16, v176
	v_lshlrev_b32_e32 v158, 16, v177
	v_and_b32_e32 v159, 0xffff0000, v177
	v_lshlrev_b32_e32 v160, 16, v179
	v_and_b32_e32 v161, 0xffff0000, v179
	v_lshlrev_b32_e32 v172, 16, v180
	v_and_b32_e32 v173, 0xffff0000, v180
	v_lshlrev_b32_e32 v162, 16, v181
	v_and_b32_e32 v163, 0xffff0000, v181
	v_lshlrev_b32_e32 v174, 16, v182
	v_and_b32_e32 v175, 0xffff0000, v182
	v_lshlrev_b32_e32 v164, 16, v183
	v_and_b32_e32 v165, 0xffff0000, v183
	v_pk_add_f32 v[128:129], v[128:129], v[158:159]
	v_pk_add_f32 v[126:127], v[126:127], v[168:169]
	v_pk_add_f32 v[124:125], v[124:125], v[160:161]
	v_pk_add_f32 v[122:123], v[122:123], v[170:171]
	v_pk_add_f32 v[120:121], v[120:121], v[162:163]
	v_pk_add_f32 v[118:119], v[118:119], v[172:173]
	v_pk_add_f32 v[158:159], v[116:117], v[164:165]
	v_pk_add_f32 v[160:161], v[114:115], v[174:175]
	v_cvt_pk_bf16_f32 v114, v126, v127
	v_cvt_pk_bf16_f32 v115, v128, v129
	v_mul_f32_e32 v116, v127, v127
	v_mul_f32_e32 v117, v129, v129
	v_mul_f32_e32 v127, v123, v123
	v_mul_f32_e32 v129, v125, v125
	v_mul_f32_e32 v162, v119, v119
	v_mul_f32_e32 v163, v121, v121
	v_mul_f32_e32 v164, v161, v161
	v_mul_f32_e32 v165, v159, v159
	v_fmac_f32_e32 v116, v126, v126
	v_fmac_f32_e32 v117, v128, v128
	v_fmac_f32_e32 v127, v122, v122
	v_fmac_f32_e32 v129, v124, v124
	v_fmac_f32_e32 v162, v118, v118
	v_fmac_f32_e32 v163, v120, v120
	v_fmac_f32_e32 v164, v160, v160
	v_fmac_f32_e32 v165, v158, v158
	v_add_f32_e32 v116, v116, v117
	v_add_f32_e32 v117, v127, v129
	v_add_f32_e32 v126, v162, v163
	v_add_f32_e32 v127, v164, v165
	v_add_f32_e32 v116, v116, v117
	v_add_f32_e32 v117, v126, v127
	v_lshlrev_b32_e32 v156, 2, v156
	v_add_f32_e32 v126, v116, v117
	ds_bpermute_b32 v127, v156, v126
	v_cvt_pk_bf16_f32 v116, v122, v123
	v_cvt_pk_bf16_f32 v117, v124, v125
	global_store_dwordx4 v[166:167], v[114:117], off
	v_cvt_pk_bf16_f32 v118, v118, v119
	v_cvt_pk_bf16_f32 v119, v120, v121
	s_waitcnt lgkmcnt(0)
	v_add_f32_e32 v114, v126, v127
	v_lshlrev_b32_e32 v116, 2, v157
	ds_bpermute_b32 v115, v116, v114
	v_cvt_pk_bf16_f32 v120, v160, v161
	v_cvt_pk_bf16_f32 v121, v158, v159
	global_store_dwordx4 v[166:167], v[118:121], off offset:256
	s_and_saveexec_b64 s[26:27], s[0:1]
	s_cbranch_execz .LBB0_1953
	s_waitcnt lgkmcnt(0)
	v_add_f32_e32 v114, v114, v115
	v_fma_f32 v114, v114, s51, 0.5
	v_cvt_u32_f32_e32 v117, v114
	v_lshl_add_u64 v[114:115], v[148:149], 2, s[10:11]
	global_atomic_add v[114:115], v117, off
; DI unsigned pk2(float lo, float hi) { f32x2 v = {lo, hi}; return __builtin_bit_cast(unsigned, __builtin_convertvector(v, bf16v2)); }
; DI void ssq_add(float* ssq, int row, float s) { atomicAdd((unsigned*)ssq + row, (unsigned)(s * 1024.f + 0.5f)); }
;     __device__ __forceinline__ void operator()(const f32x4 (&acc)[2][2][4][2], const Unit& u, int wr, int wc, int fr, int fq, const Pre&) const {
;     ...
;             for (int m = 0; m < 4; ++m) {
;                 const int row = row0 + ai * HALF + m * 16; const size_t off = (size_t)row * DM + col0; float s = 0.f;
; #pragma unroll
;                 for (int bj = 0; bj < 2; ++bj) {
;                     f32x4 b0, b1;
;                     if (BASE_F32) { const float* bp = (const float*)base + off + bj * HALF; b0 = *(const f32x4*)bp; b1 = *(const f32x4*)(bp + 4); }
;                     else { const u32x4 w = *(const u32x4*)((const bf16_t*)base + off + bj * HALF); b0 = (f32x4){bflo(w.x), bfhi(w.x), bflo(w.y), bfhi(w.y)}; b1 = (f32x4){bflo(w.z), bfhi(w.z), bflo(w.w), bfhi(w.w)}; }
;                     const f32x4 o0 = b0 + acc[ai][bj][m][0] * alpha, o1 = b1 + acc[ai][bj][m][1] * alpha;
;                     if (OUT_F32) { float* op = (float*)out + off + bj * HALF; *(f32x4*)op = o0; *(f32x4*)(op + 4) = o1; }
;                     else { u32x4 w; w.x = pk2(o0[0], o0[1]); w.y = pk2(o0[2], o0[3]); w.z = pk2(o1[0], o1[1]); w.w = pk2(o1[2], o1[3]); *(u32x4*)((bf16_t*)out + off + bj * HALF) = w; }
;                     s += ((o0[0] * o0[0] + o0[1] * o0[1]) + (o0[2] * o0[2] + o0[3] * o0[3])) + ((o1[0] * o1[0] + o1[1] * o1[1]) + (o1[2] * o1[2] + o1[3] * o1[3]));
;                 }
;                 if (ssq) { s += __shfl_xor(s, 16); s += __shfl_xor(s, 32); if (fq == 0) ssq_add(ssq, row, s); }
.LBB0_1953:
	s_or_b64 exec, exec, s[26:27]
	v_or_b32_e32 v114, 16, v148
	s_waitcnt lgkmcnt(0)
	v_ashrrev_i32_e32 v115, 31, v114
	v_readlane_b32 s26, v244, 63
	v_lshlrev_b64 v[118:119], 11, v[114:115]
	v_readlane_b32 s27, v243, 0
	s_nop 1
	v_lshl_add_u64 v[118:119], s[26:27], 0, v[118:119]
	v_lshl_add_u64 v[126:127], v[146:147], 1, v[118:119]
	s_waitcnt vmcnt(16)
	v_lshlrev_b32_e32 v128, 16, v184
	v_and_b32_e32 v129, 0xffff0000, v184
	v_lshlrev_b32_e32 v118, 16, v185
	v_and_b32_e32 v119, 0xffff0000, v185
	v_lshlrev_b32_e32 v158, 16, v186
	v_and_b32_e32 v159, 0xffff0000, v186
	v_lshlrev_b32_e32 v120, 16, v187
	v_and_b32_e32 v121, 0xffff0000, v187
	s_waitcnt vmcnt(15)
	v_lshlrev_b32_e32 v160, 16, v188
	v_and_b32_e32 v161, 0xffff0000, v188
	v_lshlrev_b32_e32 v122, 16, v189
	v_and_b32_e32 v123, 0xffff0000, v189
	v_lshlrev_b32_e32 v162, 16, v190
	v_and_b32_e32 v163, 0xffff0000, v190
	v_lshlrev_b32_e32 v124, 16, v191
	v_and_b32_e32 v125, 0xffff0000, v191
	v_pk_add_f32 v[112:113], v[112:113], v[118:119]
	v_pk_add_f32 v[110:111], v[110:111], v[128:129]
	v_pk_add_f32 v[108:109], v[108:109], v[120:121]
	v_pk_add_f32 v[106:107], v[106:107], v[158:159]
	v_pk_add_f32 v[104:105], v[104:105], v[122:123]
	v_pk_add_f32 v[102:103], v[102:103], v[160:161]
	v_pk_add_f32 v[118:119], v[100:101], v[124:125]
	v_pk_add_f32 v[120:121], v[98:99], v[162:163]
	v_cvt_pk_bf16_f32 v98, v110, v111
	v_cvt_pk_bf16_f32 v99, v112, v113
	v_mul_f32_e32 v100, v111, v111
	v_mul_f32_e32 v101, v113, v113
	v_mul_f32_e32 v111, v107, v107
	v_mul_f32_e32 v113, v109, v109
	v_mul_f32_e32 v117, v103, v103
	v_mul_f32_e32 v122, v105, v105
	v_mul_f32_e32 v123, v121, v121
	v_mul_f32_e32 v124, v119, v119
	v_fmac_f32_e32 v100, v110, v110
	v_fmac_f32_e32 v101, v112, v112
	v_fmac_f32_e32 v111, v106, v106
	v_fmac_f32_e32 v113, v108, v108
	v_fmac_f32_e32 v117, v102, v102
	v_fmac_f32_e32 v122, v104, v104
	v_fmac_f32_e32 v123, v120, v120
	v_fmac_f32_e32 v124, v118, v118
	v_add_f32_e32 v100, v100, v101
	v_add_f32_e32 v101, v111, v113
	v_add_f32_e32 v110, v117, v122
	v_add_f32_e32 v111, v123, v124
	v_add_f32_e32 v100, v100, v101
	v_add_f32_e32 v101, v110, v111
	v_add_f32_e32 v110, v100, v101
	ds_bpermute_b32 v111, v156, v110
	v_cvt_pk_bf16_f32 v100, v106, v107
	v_cvt_pk_bf16_f32 v101, v108, v109
	global_store_dwordx4 v[126:127], v[98:101], off
	s_waitcnt lgkmcnt(0)
	s_nop 0
	v_add_f32_e32 v98, v110, v111
	ds_bpermute_b32 v99, v116, v98
	v_cvt_pk_bf16_f32 v100, v102, v103
	v_cvt_pk_bf16_f32 v101, v104, v105
	v_cvt_pk_bf16_f32 v102, v120, v121
	v_cvt_pk_bf16_f32 v103, v118, v119
	global_store_dwordx4 v[126:127], v[100:103], off offset:256
	s_and_saveexec_b64 s[26:27], s[0:1]
	s_cbranch_execz .LBB0_1955
	s_waitcnt lgkmcnt(0)
	v_add_f32_e32 v98, v98, v99
	v_fma_f32 v98, v98, s51, 0.5
	v_cvt_u32_f32_e32 v100, v98
	v_lshl_add_u64 v[98:99], v[114:115], 2, s[10:11]
	global_atomic_add v[98:99], v100, off
.LBB0_1955:
	s_or_b64 exec, exec, s[26:27]
	v_or_b32_e32 v98, 32, v148
	s_waitcnt lgkmcnt(0)
	v_ashrrev_i32_e32 v99, 31, v98
	v_readlane_b32 s26, v244, 63
	v_lshlrev_b64 v[100:101], 11, v[98:99]
	v_readlane_b32 s27, v243, 0
	s_nop 1
	v_lshl_add_u64 v[100:101], s[26:27], 0, v[100:101]
	v_lshl_add_u64 v[108:109], v[146:147], 1, v[100:101]
	s_waitcnt vmcnt(17)
	v_lshlrev_b32_e32 v110, 16, v196
	v_and_b32_e32 v111, 0xffff0000, v196
	v_lshlrev_b32_e32 v100, 16, v197
	v_and_b32_e32 v101, 0xffff0000, v197
	v_lshlrev_b32_e32 v112, 16, v198
	v_and_b32_e32 v113, 0xffff0000, v198
	v_lshlrev_b32_e32 v102, 16, v199
	v_and_b32_e32 v103, 0xffff0000, v199
	s_waitcnt vmcnt(16)
	v_lshlrev_b32_e32 v114, 16, v200
	v_and_b32_e32 v115, 0xffff0000, v200
	v_lshlrev_b32_e32 v104, 16, v201
	v_and_b32_e32 v105, 0xffff0000, v201
	v_lshlrev_b32_e32 v118, 16, v202
	v_and_b32_e32 v119, 0xffff0000, v202
	v_lshlrev_b32_e32 v106, 16, v203
	v_and_b32_e32 v107, 0xffff0000, v203
	v_pk_add_f32 v[96:97], v[96:97], v[100:101]
	v_pk_add_f32 v[94:95], v[94:95], v[110:111]
	v_pk_add_f32 v[92:93], v[92:93], v[102:103]
	v_pk_add_f32 v[90:91], v[90:91], v[112:113]
	v_pk_add_f32 v[88:89], v[88:89], v[104:105]
	v_pk_add_f32 v[86:87], v[86:87], v[114:115]
	v_pk_add_f32 v[100:101], v[84:85], v[106:107]
	v_pk_add_f32 v[102:103], v[82:83], v[118:119]
	v_cvt_pk_bf16_f32 v82, v94, v95
	v_cvt_pk_bf16_f32 v83, v96, v97
	v_mul_f32_e32 v84, v95, v95
	v_mul_f32_e32 v85, v97, v97
	v_mul_f32_e32 v95, v91, v91
	v_mul_f32_e32 v97, v93, v93
	v_mul_f32_e32 v104, v87, v87
	v_mul_f32_e32 v105, v89, v89
	v_mul_f32_e32 v106, v103, v103
	v_mul_f32_e32 v107, v101, v101
	v_fmac_f32_e32 v84, v94, v94
	v_fmac_f32_e32 v85, v96, v96
	v_fmac_f32_e32 v95, v90, v90
	v_fmac_f32_e32 v97, v92, v92
	v_fmac_f32_e32 v104, v86, v86
	v_fmac_f32_e32 v105, v88, v88
	v_fmac_f32_e32 v106, v102, v102
	v_fmac_f32_e32 v107, v100, v100
	v_add_f32_e32 v84, v84, v85
	v_add_f32_e32 v85, v95, v97
	v_add_f32_e32 v94, v104, v105
	v_add_f32_e32 v95, v106, v107
	v_add_f32_e32 v84, v84, v85
	v_add_f32_e32 v85, v94, v95
	v_add_f32_e32 v94, v84, v85
	ds_bpermute_b32 v95, v156, v94
	v_cvt_pk_bf16_f32 v84, v90, v91
	v_cvt_pk_bf16_f32 v85, v92, v93
	global_store_dwordx4 v[108:109], v[82:85], off
	s_waitcnt lgkmcnt(0)
	s_nop 0
	v_add_f32_e32 v82, v94, v95
	ds_bpermute_b32 v83, v116, v82
	v_cvt_pk_bf16_f32 v84, v86, v87
	v_cvt_pk_bf16_f32 v85, v88, v89
	v_cvt_pk_bf16_f32 v86, v102, v103
	v_cvt_pk_bf16_f32 v87, v100, v101
	global_store_dwordx4 v[108:109], v[84:87], off offset:256
	s_and_saveexec_b64 s[26:27], s[0:1]
	s_cbranch_execz .LBB0_1957
	s_waitcnt lgkmcnt(0)
	v_add_f32_e32 v82, v82, v83
	v_fma_f32 v82, v82, s51, 0.5
	v_cvt_u32_f32_e32 v84, v82
	v_lshl_add_u64 v[82:83], v[98:99], 2, s[10:11]
	global_atomic_add v[82:83], v84, off
; DI unsigned pk2(float lo, float hi) { f32x2 v = {lo, hi}; return __builtin_bit_cast(unsigned, __builtin_convertvector(v, bf16v2)); }
; DI void ssq_add(float* ssq, int row, float s) { atomicAdd((unsigned*)ssq + row, (unsigned)(s * 1024.f + 0.5f)); }
;     __device__ __forceinline__ void operator()(const f32x4 (&acc)[2][2][4][2], const Unit& u, int wr, int wc, int fr, int fq, const Pre&) const {
;     ...
;             for (int m = 0; m < 4; ++m) {
;                 const int row = row0 + ai * HALF + m * 16; const size_t off = (size_t)row * DM + col0; float s = 0.f;
; #pragma unroll
;                 for (int bj = 0; bj < 2; ++bj) {
;                     f32x4 b0, b1;
;                     if (BASE_F32) { const float* bp = (const float*)base + off + bj * HALF; b0 = *(const f32x4*)bp; b1 = *(const f32x4*)(bp + 4); }
;                     else { const u32x4 w = *(const u32x4*)((const bf16_t*)base + off + bj * HALF); b0 = (f32x4){bflo(w.x), bfhi(w.x), bflo(w.y), bfhi(w.y)}; b1 = (f32x4){bflo(w.z), bfhi(w.z), bflo(w.w), bfhi(w.w)}; }
;                     const f32x4 o0 = b0 + acc[ai][bj][m][0] * alpha, o1 = b1 + acc[ai][bj][m][1] * alpha;
;                     if (OUT_F32) { float* op = (float*)out + off + bj * HALF; *(f32x4*)op = o0; *(f32x4*)(op + 4) = o1; }
;                     else { u32x4 w; w.x = pk2(o0[0], o0[1]); w.y = pk2(o0[2], o0[3]); w.z = pk2(o1[0], o1[1]); w.w = pk2(o1[2], o1[3]); *(u32x4*)((bf16_t*)out + off + bj * HALF) = w; }
;                     s += ((o0[0] * o0[0] + o0[1] * o0[1]) + (o0[2] * o0[2] + o0[3] * o0[3])) + ((o1[0] * o1[0] + o1[1] * o1[1]) + (o1[2] * o1[2] + o1[3] * o1[3]));
;                 }
;                 if (ssq) { s += __shfl_xor(s, 16); s += __shfl_xor(s, 32); if (fq == 0) ssq_add(ssq, row, s); }
.LBB0_1957:
	s_or_b64 exec, exec, s[26:27]
	v_or_b32_e32 v82, 48, v148
	s_waitcnt lgkmcnt(0)
	v_ashrrev_i32_e32 v83, 31, v82
	v_readlane_b32 s26, v244, 63
	v_lshlrev_b64 v[84:85], 11, v[82:83]
	v_readlane_b32 s27, v243, 0
	s_nop 1
	v_lshl_add_u64 v[84:85], s[26:27], 0, v[84:85]
	v_lshl_add_u64 v[92:93], v[146:147], 1, v[84:85]
	s_waitcnt vmcnt(18)
	v_lshlrev_b32_e32 v94, 16, v204
	v_and_b32_e32 v95, 0xffff0000, v204
	v_lshlrev_b32_e32 v84, 16, v205
	v_and_b32_e32 v85, 0xffff0000, v205
	v_lshlrev_b32_e32 v96, 16, v206
	v_and_b32_e32 v97, 0xffff0000, v206
	v_lshlrev_b32_e32 v86, 16, v207
	v_and_b32_e32 v87, 0xffff0000, v207
	s_waitcnt vmcnt(17)
	v_lshlrev_b32_e32 v98, 16, v208
	v_and_b32_e32 v99, 0xffff0000, v208
	v_lshlrev_b32_e32 v88, 16, v209
	v_and_b32_e32 v89, 0xffff0000, v209
	v_lshlrev_b32_e32 v100, 16, v210
	v_and_b32_e32 v101, 0xffff0000, v210
	v_lshlrev_b32_e32 v90, 16, v211
	v_and_b32_e32 v91, 0xffff0000, v211
	v_pk_add_f32 v[80:81], v[80:81], v[84:85]
	v_pk_add_f32 v[78:79], v[78:79], v[94:95]
	v_pk_add_f32 v[76:77], v[76:77], v[86:87]
	v_pk_add_f32 v[74:75], v[74:75], v[96:97]
	v_pk_add_f32 v[72:73], v[72:73], v[88:89]
	v_pk_add_f32 v[70:71], v[70:71], v[98:99]
	v_pk_add_f32 v[84:85], v[68:69], v[90:91]
	v_pk_add_f32 v[86:87], v[66:67], v[100:101]
	v_cvt_pk_bf16_f32 v66, v78, v79
	v_cvt_pk_bf16_f32 v67, v80, v81
	v_mul_f32_e32 v68, v79, v79
	v_mul_f32_e32 v69, v81, v81
	v_mul_f32_e32 v79, v75, v75
	v_mul_f32_e32 v81, v77, v77
	v_mul_f32_e32 v88, v71, v71
	v_mul_f32_e32 v89, v73, v73
	v_mul_f32_e32 v90, v87, v87
	v_mul_f32_e32 v91, v85, v85
	v_fmac_f32_e32 v68, v78, v78
	v_fmac_f32_e32 v69, v80, v80
	v_fmac_f32_e32 v79, v74, v74
	v_fmac_f32_e32 v81, v76, v76
	v_fmac_f32_e32 v88, v70, v70
	v_fmac_f32_e32 v89, v72, v72
	v_fmac_f32_e32 v90, v86, v86
	v_fmac_f32_e32 v91, v84, v84
	v_add_f32_e32 v68, v68, v69
	v_add_f32_e32 v69, v79, v81
	v_add_f32_e32 v78, v88, v89
	v_add_f32_e32 v79, v90, v91
	v_add_f32_e32 v68, v68, v69
	v_add_f32_e32 v69, v78, v79
	v_add_f32_e32 v78, v68, v69
	ds_bpermute_b32 v79, v156, v78
	v_cvt_pk_bf16_f32 v68, v74, v75
	v_cvt_pk_bf16_f32 v69, v76, v77
	global_store_dwordx4 v[92:93], v[66:69], off
	s_waitcnt lgkmcnt(0)
	s_nop 0
	v_add_f32_e32 v66, v78, v79
	ds_bpermute_b32 v67, v116, v66
	v_cvt_pk_bf16_f32 v68, v70, v71
	v_cvt_pk_bf16_f32 v69, v72, v73
	v_cvt_pk_bf16_f32 v70, v86, v87
	v_cvt_pk_bf16_f32 v71, v84, v85
	global_store_dwordx4 v[92:93], v[68:71], off offset:256
	s_and_saveexec_b64 s[26:27], s[0:1]
	s_cbranch_execz .LBB0_1959
	s_waitcnt lgkmcnt(0)
	v_add_f32_e32 v66, v66, v67
	v_fma_f32 v66, v66, s51, 0.5
	v_cvt_u32_f32_e32 v68, v66
	v_lshl_add_u64 v[66:67], v[82:83], 2, s[10:11]
	global_atomic_add v[66:67], v68, off
.LBB0_1959:
	s_or_b64 exec, exec, s[26:27]
	v_add_u32_e32 v66, 0x80, v148
	s_waitcnt lgkmcnt(0)
	v_ashrrev_i32_e32 v67, 31, v66
	v_readlane_b32 s26, v244, 63
	v_lshlrev_b64 v[68:69], 11, v[66:67]
	v_readlane_b32 s27, v243, 0
	s_nop 1
	v_lshl_add_u64 v[68:69], s[26:27], 0, v[68:69]
	v_lshl_add_u64 v[76:77], v[146:147], 1, v[68:69]
	s_waitcnt vmcnt(19)
	v_lshlrev_b32_e32 v78, 16, v212
	v_and_b32_e32 v79, 0xffff0000, v212
	v_lshlrev_b32_e32 v68, 16, v213
	v_and_b32_e32 v69, 0xffff0000, v213
	v_lshlrev_b32_e32 v80, 16, v214
	v_and_b32_e32 v81, 0xffff0000, v214
	v_lshlrev_b32_e32 v70, 16, v215
	v_and_b32_e32 v71, 0xffff0000, v215
	s_waitcnt vmcnt(18)
	v_lshlrev_b32_e32 v82, 16, v216
	v_and_b32_e32 v83, 0xffff0000, v216
	v_lshlrev_b32_e32 v72, 16, v217
	v_and_b32_e32 v73, 0xffff0000, v217
	v_lshlrev_b32_e32 v84, 16, v218
	v_and_b32_e32 v85, 0xffff0000, v218
	v_lshlrev_b32_e32 v74, 16, v219
	v_and_b32_e32 v75, 0xffff0000, v219
	v_pk_add_f32 v[64:65], v[64:65], v[68:69]
	v_pk_add_f32 v[62:63], v[62:63], v[78:79]
	v_pk_add_f32 v[60:61], v[60:61], v[70:71]
	v_pk_add_f32 v[58:59], v[58:59], v[80:81]
	v_pk_add_f32 v[56:57], v[56:57], v[72:73]
	v_pk_add_f32 v[54:55], v[54:55], v[82:83]
	v_pk_add_f32 v[68:69], v[52:53], v[74:75]
	v_pk_add_f32 v[70:71], v[50:51], v[84:85]
	v_cvt_pk_bf16_f32 v50, v62, v63
	v_cvt_pk_bf16_f32 v51, v64, v65
	v_mul_f32_e32 v52, v63, v63
	v_mul_f32_e32 v53, v65, v65
	v_mul_f32_e32 v63, v59, v59
	v_mul_f32_e32 v65, v61, v61
	v_mul_f32_e32 v72, v55, v55
	v_mul_f32_e32 v73, v57, v57
	v_mul_f32_e32 v74, v71, v71
	v_mul_f32_e32 v75, v69, v69
	v_fmac_f32_e32 v52, v62, v62
	v_fmac_f32_e32 v53, v64, v64
	v_fmac_f32_e32 v63, v58, v58
	v_fmac_f32_e32 v65, v60, v60
	v_fmac_f32_e32 v72, v54, v54
	v_fmac_f32_e32 v73, v56, v56
	v_fmac_f32_e32 v74, v70, v70
	v_fmac_f32_e32 v75, v68, v68
	v_add_f32_e32 v52, v52, v53
	v_add_f32_e32 v53, v63, v65
	v_add_f32_e32 v62, v72, v73
	v_add_f32_e32 v63, v74, v75
	v_add_f32_e32 v52, v52, v53
	v_add_f32_e32 v53, v62, v63
	v_add_f32_e32 v62, v52, v53
	ds_bpermute_b32 v63, v156, v62
	v_cvt_pk_bf16_f32 v52, v58, v59
	v_cvt_pk_bf16_f32 v53, v60, v61
	global_store_dwordx4 v[76:77], v[50:53], off
	s_waitcnt lgkmcnt(0)
	s_nop 0
	v_add_f32_e32 v50, v62, v63
	ds_bpermute_b32 v51, v116, v50
	v_cvt_pk_bf16_f32 v52, v54, v55
	v_cvt_pk_bf16_f32 v53, v56, v57
	v_cvt_pk_bf16_f32 v54, v70, v71
	v_cvt_pk_bf16_f32 v55, v68, v69
	global_store_dwordx4 v[76:77], v[52:55], off offset:256
	s_and_saveexec_b64 s[26:27], s[0:1]
	s_cbranch_execz .LBB0_1961
	s_waitcnt lgkmcnt(0)
	v_add_f32_e32 v50, v50, v51
	v_fma_f32 v50, v50, s51, 0.5
	v_cvt_u32_f32_e32 v52, v50
	v_lshl_add_u64 v[50:51], v[66:67], 2, s[10:11]
	global_atomic_add v[50:51], v52, off
; DI unsigned pk2(float lo, float hi) { f32x2 v = {lo, hi}; return __builtin_bit_cast(unsigned, __builtin_convertvector(v, bf16v2)); }
; DI void ssq_add(float* ssq, int row, float s) { atomicAdd((unsigned*)ssq + row, (unsigned)(s * 1024.f + 0.5f)); }
;     __device__ __forceinline__ void operator()(const f32x4 (&acc)[2][2][4][2], const Unit& u, int wr, int wc, int fr, int fq, const Pre&) const {
;     ...
;             for (int m = 0; m < 4; ++m) {
;                 const int row = row0 + ai * HALF + m * 16; const size_t off = (size_t)row * DM + col0; float s = 0.f;
; #pragma unroll
;                 for (int bj = 0; bj < 2; ++bj) {
;                     f32x4 b0, b1;
;                     if (BASE_F32) { const float* bp = (const float*)base + off + bj * HALF; b0 = *(const f32x4*)bp; b1 = *(const f32x4*)(bp + 4); }
;                     else { const u32x4 w = *(const u32x4*)((const bf16_t*)base + off + bj * HALF); b0 = (f32x4){bflo(w.x), bfhi(w.x), bflo(w.y), bfhi(w.y)}; b1 = (f32x4){bflo(w.z), bfhi(w.z), bflo(w.w), bfhi(w.w)}; }
;                     const f32x4 o0 = b0 + acc[ai][bj][m][0] * alpha, o1 = b1 + acc[ai][bj][m][1] * alpha;
;                     if (OUT_F32) { float* op = (float*)out + off + bj * HALF; *(f32x4*)op = o0; *(f32x4*)(op + 4) = o1; }
;                     else { u32x4 w; w.x = pk2(o0[0], o0[1]); w.y = pk2(o0[2], o0[3]); w.z = pk2(o1[0], o1[1]); w.w = pk2(o1[2], o1[3]); *(u32x4*)((bf16_t*)out + off + bj * HALF) = w; }
;                     s += ((o0[0] * o0[0] + o0[1] * o0[1]) + (o0[2] * o0[2] + o0[3] * o0[3])) + ((o1[0] * o1[0] + o1[1] * o1[1]) + (o1[2] * o1[2] + o1[3] * o1[3]));
;                 }
;                 if (ssq) { s += __shfl_xor(s, 16); s += __shfl_xor(s, 32); if (fq == 0) ssq_add(ssq, row, s); }
.LBB0_1961:
	s_or_b64 exec, exec, s[26:27]
	v_add_u32_e32 v50, 0x90, v148
	s_waitcnt lgkmcnt(0)
	v_ashrrev_i32_e32 v51, 31, v50
	v_readlane_b32 s26, v244, 63
	v_lshlrev_b64 v[52:53], 11, v[50:51]
	v_readlane_b32 s27, v243, 0
	s_nop 1
	v_lshl_add_u64 v[52:53], s[26:27], 0, v[52:53]
	v_lshl_add_u64 v[60:61], v[146:147], 1, v[52:53]
	s_waitcnt vmcnt(20)
	v_lshlrev_b32_e32 v62, 16, v220
	v_and_b32_e32 v63, 0xffff0000, v220
	v_lshlrev_b32_e32 v52, 16, v221
	v_and_b32_e32 v53, 0xffff0000, v221
	v_lshlrev_b32_e32 v64, 16, v222
	v_and_b32_e32 v65, 0xffff0000, v222
	v_lshlrev_b32_e32 v54, 16, v223
	v_and_b32_e32 v55, 0xffff0000, v223
	s_waitcnt vmcnt(19)
	v_lshlrev_b32_e32 v66, 16, v224
	v_and_b32_e32 v67, 0xffff0000, v224
	v_lshlrev_b32_e32 v56, 16, v225
	v_and_b32_e32 v57, 0xffff0000, v225
	v_lshlrev_b32_e32 v68, 16, v226
	v_and_b32_e32 v69, 0xffff0000, v226
	v_lshlrev_b32_e32 v58, 16, v227
	v_and_b32_e32 v59, 0xffff0000, v227
	v_pk_add_f32 v[48:49], v[48:49], v[52:53]
	v_pk_add_f32 v[46:47], v[46:47], v[62:63]
	v_pk_add_f32 v[44:45], v[44:45], v[54:55]
	v_pk_add_f32 v[42:43], v[42:43], v[64:65]
	v_pk_add_f32 v[40:41], v[40:41], v[56:57]
	v_pk_add_f32 v[38:39], v[38:39], v[66:67]
	v_pk_add_f32 v[52:53], v[36:37], v[58:59]
	v_pk_add_f32 v[54:55], v[34:35], v[68:69]
	v_cvt_pk_bf16_f32 v34, v46, v47
	v_cvt_pk_bf16_f32 v35, v48, v49
	v_mul_f32_e32 v36, v47, v47
	v_mul_f32_e32 v37, v49, v49
	v_mul_f32_e32 v47, v43, v43
	v_mul_f32_e32 v49, v45, v45
	v_mul_f32_e32 v56, v39, v39
	v_mul_f32_e32 v57, v41, v41
	v_mul_f32_e32 v58, v55, v55
	v_mul_f32_e32 v59, v53, v53
	v_fmac_f32_e32 v36, v46, v46
	v_fmac_f32_e32 v37, v48, v48
	v_fmac_f32_e32 v47, v42, v42
	v_fmac_f32_e32 v49, v44, v44
	v_fmac_f32_e32 v56, v38, v38
	v_fmac_f32_e32 v57, v40, v40
	v_fmac_f32_e32 v58, v54, v54
	v_fmac_f32_e32 v59, v52, v52
	v_add_f32_e32 v36, v36, v37
	v_add_f32_e32 v37, v47, v49
	v_add_f32_e32 v46, v56, v57
	v_add_f32_e32 v47, v58, v59
	v_add_f32_e32 v36, v36, v37
	v_add_f32_e32 v37, v46, v47
	v_add_f32_e32 v46, v36, v37
	ds_bpermute_b32 v47, v156, v46
	v_cvt_pk_bf16_f32 v36, v42, v43
	v_cvt_pk_bf16_f32 v37, v44, v45
	global_store_dwordx4 v[60:61], v[34:37], off
	s_waitcnt lgkmcnt(0)
	s_nop 0
	v_add_f32_e32 v34, v46, v47
	ds_bpermute_b32 v35, v116, v34
	v_cvt_pk_bf16_f32 v36, v38, v39
	v_cvt_pk_bf16_f32 v37, v40, v41
	v_cvt_pk_bf16_f32 v38, v54, v55
	v_cvt_pk_bf16_f32 v39, v52, v53
	global_store_dwordx4 v[60:61], v[36:39], off offset:256
	s_and_saveexec_b64 s[26:27], s[0:1]
	s_cbranch_execz .LBB0_1963
	s_waitcnt lgkmcnt(0)
	v_add_f32_e32 v34, v34, v35
	v_fma_f32 v34, v34, s51, 0.5
	v_cvt_u32_f32_e32 v36, v34
	v_lshl_add_u64 v[34:35], v[50:51], 2, s[10:11]
	global_atomic_add v[34:35], v36, off
; DI unsigned pk2(float lo, float hi) { f32x2 v = {lo, hi}; return __builtin_bit_cast(unsigned, __builtin_convertvector(v, bf16v2)); }
; DI void ssq_add(float* ssq, int row, float s) { atomicAdd((unsigned*)ssq + row, (unsigned)(s * 1024.f + 0.5f)); }
;     __device__ __forceinline__ void operator()(const f32x4 (&acc)[2][2][4][2], const Unit& u, int wr, int wc, int fr, int fq, const Pre&) const {
;     ...
;             for (int m = 0; m < 4; ++m) {
;                 const int row = row0 + ai * HALF + m * 16; const size_t off = (size_t)row * DM + col0; float s = 0.f;
; #pragma unroll
;                 for (int bj = 0; bj < 2; ++bj) {
;                     f32x4 b0, b1;
;                     if (BASE_F32) { const float* bp = (const float*)base + off + bj * HALF; b0 = *(const f32x4*)bp; b1 = *(const f32x4*)(bp + 4); }
;                     else { const u32x4 w = *(const u32x4*)((const bf16_t*)base + off + bj * HALF); b0 = (f32x4){bflo(w.x), bfhi(w.x), bflo(w.y), bfhi(w.y)}; b1 = (f32x4){bflo(w.z), bfhi(w.z), bflo(w.w), bfhi(w.w)}; }
;                     const f32x4 o0 = b0 + acc[ai][bj][m][0] * alpha, o1 = b1 + acc[ai][bj][m][1] * alpha;
;                     if (OUT_F32) { float* op = (float*)out + off + bj * HALF; *(f32x4*)op = o0; *(f32x4*)(op + 4) = o1; }
;                     else { u32x4 w; w.x = pk2(o0[0], o0[1]); w.y = pk2(o0[2], o0[3]); w.z = pk2(o1[0], o1[1]); w.w = pk2(o1[2], o1[3]); *(u32x4*)((bf16_t*)out + off + bj * HALF) = w; }
;                     s += ((o0[0] * o0[0] + o0[1] * o0[1]) + (o0[2] * o0[2] + o0[3] * o0[3])) + ((o1[0] * o1[0] + o1[1] * o1[1]) + (o1[2] * o1[2] + o1[3] * o1[3]));
;                 }
;                 if (ssq) { s += __shfl_xor(s, 16); s += __shfl_xor(s, 32); if (fq == 0) ssq_add(ssq, row, s); }
.LBB0_1963:
	s_or_b64 exec, exec, s[26:27]
	v_add_u32_e32 v34, 0xa0, v148
	s_waitcnt lgkmcnt(0)
	v_ashrrev_i32_e32 v35, 31, v34
	v_readlane_b32 s26, v244, 63
	v_lshlrev_b64 v[36:37], 11, v[34:35]
	v_readlane_b32 s27, v243, 0
	s_nop 1
	v_lshl_add_u64 v[36:37], s[26:27], 0, v[36:37]
	v_lshl_add_u64 v[44:45], v[146:147], 1, v[36:37]
	s_waitcnt vmcnt(21)
	v_lshlrev_b32_e32 v46, 16, v228
	v_and_b32_e32 v47, 0xffff0000, v228
	v_lshlrev_b32_e32 v36, 16, v229
	v_and_b32_e32 v37, 0xffff0000, v229
	v_lshlrev_b32_e32 v48, 16, v230
	v_and_b32_e32 v49, 0xffff0000, v230
	v_lshlrev_b32_e32 v38, 16, v231
	v_and_b32_e32 v39, 0xffff0000, v231
	s_waitcnt vmcnt(20)
	v_lshlrev_b32_e32 v50, 16, v232
	v_and_b32_e32 v51, 0xffff0000, v232
	v_lshlrev_b32_e32 v40, 16, v233
	v_and_b32_e32 v41, 0xffff0000, v233
	v_lshlrev_b32_e32 v52, 16, v234
	v_and_b32_e32 v53, 0xffff0000, v234
	v_lshlrev_b32_e32 v42, 16, v235
	v_and_b32_e32 v43, 0xffff0000, v235
	v_pk_add_f32 v[32:33], v[32:33], v[36:37]
	v_pk_add_f32 v[30:31], v[30:31], v[46:47]
	v_pk_add_f32 v[28:29], v[28:29], v[38:39]
	v_pk_add_f32 v[26:27], v[26:27], v[48:49]
	v_pk_add_f32 v[24:25], v[24:25], v[40:41]
	v_pk_add_f32 v[22:23], v[22:23], v[50:51]
	v_pk_add_f32 v[36:37], v[20:21], v[42:43]
	v_pk_add_f32 v[38:39], v[18:19], v[52:53]
	v_cvt_pk_bf16_f32 v18, v30, v31
	v_cvt_pk_bf16_f32 v19, v32, v33
	v_mul_f32_e32 v20, v31, v31
	v_mul_f32_e32 v21, v33, v33
	v_mul_f32_e32 v31, v27, v27
	v_mul_f32_e32 v33, v29, v29
	v_mul_f32_e32 v40, v23, v23
	v_mul_f32_e32 v41, v25, v25
	v_mul_f32_e32 v42, v39, v39
	v_mul_f32_e32 v43, v37, v37
	v_fmac_f32_e32 v20, v30, v30
	v_fmac_f32_e32 v21, v32, v32
	v_fmac_f32_e32 v31, v26, v26
	v_fmac_f32_e32 v33, v28, v28
	v_fmac_f32_e32 v40, v22, v22
	v_fmac_f32_e32 v41, v24, v24
	v_fmac_f32_e32 v42, v38, v38
	v_fmac_f32_e32 v43, v36, v36
	v_add_f32_e32 v20, v20, v21
	v_add_f32_e32 v21, v31, v33
	v_add_f32_e32 v30, v40, v41
	v_add_f32_e32 v31, v42, v43
	v_add_f32_e32 v20, v20, v21
	v_add_f32_e32 v21, v30, v31
	v_add_f32_e32 v30, v20, v21
	ds_bpermute_b32 v31, v156, v30
	v_cvt_pk_bf16_f32 v20, v26, v27
	v_cvt_pk_bf16_f32 v21, v28, v29
	global_store_dwordx4 v[44:45], v[18:21], off
	s_waitcnt lgkmcnt(0)
	s_nop 0
	v_add_f32_e32 v18, v30, v31
	ds_bpermute_b32 v19, v116, v18
	v_cvt_pk_bf16_f32 v20, v22, v23
	v_cvt_pk_bf16_f32 v21, v24, v25
	v_cvt_pk_bf16_f32 v22, v38, v39
	v_cvt_pk_bf16_f32 v23, v36, v37
	global_store_dwordx4 v[44:45], v[20:23], off offset:256
	s_and_saveexec_b64 s[26:27], s[0:1]
	s_cbranch_execz .LBB0_1965
	s_waitcnt lgkmcnt(0)
	v_add_f32_e32 v18, v18, v19
	v_fma_f32 v18, v18, s51, 0.5
	v_cvt_u32_f32_e32 v20, v18
	v_lshl_add_u64 v[18:19], v[34:35], 2, s[10:11]
	global_atomic_add v[18:19], v20, off
.LBB0_1965:
	s_or_b64 exec, exec, s[26:27]
	v_add_u32_e32 v18, 0xb0, v148
	s_waitcnt lgkmcnt(0)
	v_ashrrev_i32_e32 v19, 31, v18
	v_readlane_b32 s26, v244, 63
	v_lshlrev_b64 v[20:21], 11, v[18:19]
	v_readlane_b32 s27, v243, 0
	s_nop 1
	v_lshl_add_u64 v[20:21], s[26:27], 0, v[20:21]
	v_lshl_add_u64 v[28:29], v[146:147], 1, v[20:21]
	s_waitcnt vmcnt(22)
	v_lshlrev_b32_e32 v30, 16, v236
	v_and_b32_e32 v31, 0xffff0000, v236
	v_lshlrev_b32_e32 v20, 16, v237
	v_and_b32_e32 v21, 0xffff0000, v237
	v_lshlrev_b32_e32 v32, 16, v238
	v_and_b32_e32 v33, 0xffff0000, v238
	v_lshlrev_b32_e32 v22, 16, v239
	v_and_b32_e32 v23, 0xffff0000, v239
	s_waitcnt vmcnt(21)
	v_lshlrev_b32_e32 v34, 16, v248
	v_and_b32_e32 v35, 0xffff0000, v248
	v_lshlrev_b32_e32 v24, 16, v249
	v_and_b32_e32 v25, 0xffff0000, v249
	v_lshlrev_b32_e32 v36, 16, v250
	v_and_b32_e32 v37, 0xffff0000, v250
	v_lshlrev_b32_e32 v26, 16, v251
	v_and_b32_e32 v27, 0xffff0000, v251
	v_pk_add_f32 v[16:17], v[16:17], v[20:21]
	v_pk_add_f32 v[14:15], v[14:15], v[30:31]
	v_pk_add_f32 v[12:13], v[12:13], v[22:23]
	v_pk_add_f32 v[10:11], v[10:11], v[32:33]
	v_pk_add_f32 v[8:9], v[8:9], v[24:25]
	v_pk_add_f32 v[6:7], v[6:7], v[34:35]
	v_pk_add_f32 v[20:21], v[4:5], v[26:27]
	v_pk_add_f32 v[22:23], v[2:3], v[36:37]
	v_cvt_pk_bf16_f32 v2, v14, v15
	v_cvt_pk_bf16_f32 v3, v16, v17
	v_mul_f32_e32 v4, v15, v15
	v_mul_f32_e32 v5, v17, v17
	v_mul_f32_e32 v15, v11, v11
	v_mul_f32_e32 v17, v13, v13
	v_mul_f32_e32 v24, v7, v7
	v_mul_f32_e32 v25, v9, v9
	v_mul_f32_e32 v26, v23, v23
	v_mul_f32_e32 v27, v21, v21
	v_fmac_f32_e32 v4, v14, v14
	v_fmac_f32_e32 v5, v16, v16
	v_fmac_f32_e32 v15, v10, v10
	v_fmac_f32_e32 v17, v12, v12
	v_fmac_f32_e32 v24, v6, v6
	v_fmac_f32_e32 v25, v8, v8
	v_fmac_f32_e32 v26, v22, v22
	v_fmac_f32_e32 v27, v20, v20
	v_add_f32_e32 v4, v4, v5
	v_add_f32_e32 v5, v15, v17
	v_add_f32_e32 v14, v24, v25
	v_add_f32_e32 v15, v26, v27
	v_add_f32_e32 v4, v4, v5
	v_add_f32_e32 v5, v14, v15
	v_add_f32_e32 v14, v4, v5
	ds_bpermute_b32 v15, v156, v14
	v_cvt_pk_bf16_f32 v4, v10, v11
	v_cvt_pk_bf16_f32 v5, v12, v13
	global_store_dwordx4 v[28:29], v[2:5], off
	s_waitcnt lgkmcnt(0)
	s_nop 0
	v_add_f32_e32 v2, v14, v15
	ds_bpermute_b32 v3, v116, v2
	v_cvt_pk_bf16_f32 v4, v6, v7
	v_cvt_pk_bf16_f32 v5, v8, v9
	v_cvt_pk_bf16_f32 v6, v22, v23
	v_cvt_pk_bf16_f32 v7, v20, v21
	global_store_dwordx4 v[28:29], v[4:7], off offset:256
	s_and_saveexec_b64 s[26:27], s[0:1]
	s_cbranch_execz .LBB0_1967
	s_waitcnt lgkmcnt(0)
	v_add_f32_e32 v2, v2, v3
	v_fma_f32 v2, v2, s51, 0.5
	v_cvt_u32_f32_e32 v4, v2
	v_lshl_add_u64 v[2:3], v[18:19], 2, s[10:11]
	global_atomic_add v[2:3], v4, off
